# v100 + EpiResid epilogue pipeline deepened to 8 loads in flight by reusing already-stored accumulator registers as load buffers
# baseline (speedup 1.0000x reference)
.LBB0_279:
	v_readlane_b32 s28, v250, 53
	s_nop 3
	s_cmp_eq_u32 s28, 3
	s_cbranch_scc1 .Lepi_A_final
	v_lshl_add_u32 v136, s58, 8, v158
	v_lshl_or_b32 v137, s2, 8, v159
	v_lshlrev_b32_e32 v136, 3, v136
	v_lshlrev_b32_e32 v137, 2, v137
	s_ashr_i32 s59, s58, 31
	s_lshl_b64 s[28:29], s[58:59], 20
	s_add_u32 s60, s73, s28
	s_addc_u32 s61, s72, s29
	v_readlane_b32 s4, v252, 0
	v_readlane_b32 s5, v252, 1
	v_readlane_b32 s6, v252, 2
	v_readlane_b32 s7, v252, 3
	v_readlane_b32 s8, v252, 4
	v_readlane_b32 s9, v252, 5
	v_readlane_b32 s10, v252, 6
	v_readlane_b32 s11, v252, 7
	v_readlane_b32 s12, v252, 8
	v_readlane_b32 s13, v252, 9
	v_readlane_b32 s14, v252, 10
	v_readlane_b32 s15, v252, 11
	v_readlane_b32 s16, v252, 12
	v_readlane_b32 s17, v252, 13
	s_mov_b64 s[4:5], s[8:9]
	v_readlane_b32 s18, v252, 14
	v_readlane_b32 s19, v252, 15
	s_mov_b64 s[6:7], s[10:11]
	s_mov_b64 s[8:9], s[12:13]
	s_mov_b64 s[12:13], s[16:17]
	s_add_u32 s58, s12, s28
	s_addc_u32 s59, s13, s29
	s_mov_b64 s[14:15], s[18:19]
	s_and_b64 vcc, exec, s[80:81]
	s_cbranch_vccz .Lepi_A_nostats
	s_mov_b64 s[40:41], 0
	global_load_dwordx2 v[240:241], v136, s[92:93]
	global_load_dwordx2 v[242:243], v136, s[92:93] offset:128
	global_load_dwordx2 v[244:245], v136, s[92:93] offset:256
	global_load_dwordx2 v[246:247], v136, s[92:93] offset:384
	global_load_dwordx2 v[248:249], v136, s[92:93] offset:1024
	global_load_dwordx2 v[220:221], v136, s[92:93] offset:1152
	global_load_dwordx2 v[108:109], v136, s[92:93] offset:1280
	global_load_dwordx2 v[110:111], v136, s[92:93] offset:1408
	global_load_dwordx4 v[196:199], v137, s[48:49]
	global_load_dwordx4 v[200:203], v137, s[84:85]
	global_load_dwordx4 v[204:207], v137, s[48:49] offset:64
	global_load_dwordx4 v[208:211], v137, s[84:85] offset:64
	global_load_dwordx4 v[212:215], v137, s[48:49] offset:512
	global_load_dwordx4 v[216:219], v137, s[84:85] offset:512
	global_load_dwordx4 v[232:235], v137, s[48:49] offset:576
	global_load_dwordx4 v[236:239], v137, s[84:85] offset:576
	v_lshl_add_u32 v112, v160, 2, v137
	v_lshl_add_u32 v113, v164, 2, v137
	v_lshl_add_u32 v130, v166, 2, v137
	v_lshl_add_u32 v131, v168, 2, v137
	v_lshl_add_u32 v132, v162, 2, v137
	v_lshl_add_u32 v133, v170, 2, v137
	v_lshl_add_u32 v134, v172, 2, v137
	v_lshl_add_u32 v135, v174, 2, v137
	global_load_dwordx4 v[180:183], v112, s[60:61]
	global_load_dwordx4 v[184:187], v112, s[60:61] offset:64
	global_load_dwordx4 v[188:191], v113, s[60:61]
	global_load_dwordx4 v[192:195], v113, s[60:61] offset:64
	s_waitcnt vmcnt(3)
	v_pk_add_f32 v[180:181], v[180:181], v[240:241] op_sel_hi:[1,0] neg_lo:[0,1] neg_hi:[0,1]
	v_pk_add_f32 v[182:183], v[182:183], v[240:241] op_sel_hi:[1,0] neg_lo:[0,1] neg_hi:[0,1]
	v_pk_mul_f32 v[180:181], v[180:181], v[240:241] op_sel:[0,1] op_sel_hi:[1,1]
	v_pk_mul_f32 v[182:183], v[182:183], v[240:241] op_sel:[0,1] op_sel_hi:[1,1]
	v_pk_fma_f32 v[180:181], v[196:197], v[180:181], v[200:201]
	v_pk_fma_f32 v[182:183], v[198:199], v[182:183], v[202:203]
	v_pk_mul_f32 v[180:181], v[180:181], s[82:83] op_sel_hi:[1,0]
	v_pk_mul_f32 v[182:183], v[182:183], s[82:83] op_sel_hi:[1,0]
	v_pk_fma_f32 v[138:139], v[138:139], 0.5, v[180:181] op_sel_hi:[1,0,1]
	v_pk_fma_f32 v[140:141], v[140:141], 0.5, v[182:183] op_sel_hi:[1,0,1]
	s_nop 0
	global_store_dwordx4 v112, v[138:141], s[58:59] sc1
	s_nop 1
	global_load_dwordx4 v[180:183], v130, s[60:61]
	global_load_dwordx4 v[138:141], v132, s[60:61]
	s_waitcnt vmcnt(5)
	v_pk_add_f32 v[184:185], v[184:185], v[240:241] op_sel_hi:[1,0] neg_lo:[0,1] neg_hi:[0,1]
	v_pk_add_f32 v[186:187], v[186:187], v[240:241] op_sel_hi:[1,0] neg_lo:[0,1] neg_hi:[0,1]
	v_pk_mul_f32 v[184:185], v[184:185], v[240:241] op_sel:[0,1] op_sel_hi:[1,1]
	v_pk_mul_f32 v[186:187], v[186:187], v[240:241] op_sel:[0,1] op_sel_hi:[1,1]
	v_pk_fma_f32 v[184:185], v[204:205], v[184:185], v[208:209]
	v_pk_fma_f32 v[186:187], v[206:207], v[186:187], v[210:211]
	v_pk_mul_f32 v[184:185], v[184:185], s[82:83] op_sel_hi:[1,0]
	v_pk_mul_f32 v[186:187], v[186:187], s[82:83] op_sel_hi:[1,0]
	v_pk_fma_f32 v[92:93], v[92:93], 0.5, v[184:185] op_sel_hi:[1,0,1]
	v_pk_fma_f32 v[94:95], v[94:95], 0.5, v[186:187] op_sel_hi:[1,0,1]
	s_nop 0
	global_store_dwordx4 v112, v[92:95], s[58:59] offset:64 sc1
	s_nop 1
	global_load_dwordx4 v[184:187], v130, s[60:61] offset:64
	global_load_dwordx4 v[92:95], v132, s[60:61] offset:64
	s_waitcnt vmcnt(7)
	v_pk_add_f32 v[188:189], v[188:189], v[242:243] op_sel_hi:[1,0] neg_lo:[0,1] neg_hi:[0,1]
	v_pk_add_f32 v[190:191], v[190:191], v[242:243] op_sel_hi:[1,0] neg_lo:[0,1] neg_hi:[0,1]
	v_pk_mul_f32 v[188:189], v[188:189], v[242:243] op_sel:[0,1] op_sel_hi:[1,1]
	v_pk_mul_f32 v[190:191], v[190:191], v[242:243] op_sel:[0,1] op_sel_hi:[1,1]
	v_pk_fma_f32 v[188:189], v[196:197], v[188:189], v[200:201]
	v_pk_fma_f32 v[190:191], v[198:199], v[190:191], v[202:203]
	v_pk_mul_f32 v[188:189], v[188:189], s[82:83] op_sel_hi:[1,0]
	v_pk_mul_f32 v[190:191], v[190:191], s[82:83] op_sel_hi:[1,0]
	v_pk_fma_f32 v[126:127], v[126:127], 0.5, v[188:189] op_sel_hi:[1,0,1]
	v_pk_fma_f32 v[128:129], v[128:129], 0.5, v[190:191] op_sel_hi:[1,0,1]
	s_nop 0
	global_store_dwordx4 v113, v[126:129], s[58:59] sc1
	s_nop 1
	global_load_dwordx4 v[188:191], v131, s[60:61]
	global_load_dwordx4 v[126:129], v133, s[60:61]
	s_waitcnt vmcnt(9)
	v_pk_add_f32 v[192:193], v[192:193], v[242:243] op_sel_hi:[1,0] neg_lo:[0,1] neg_hi:[0,1]
	v_pk_add_f32 v[194:195], v[194:195], v[242:243] op_sel_hi:[1,0] neg_lo:[0,1] neg_hi:[0,1]
	v_pk_mul_f32 v[192:193], v[192:193], v[242:243] op_sel:[0,1] op_sel_hi:[1,1]
	v_pk_mul_f32 v[194:195], v[194:195], v[242:243] op_sel:[0,1] op_sel_hi:[1,1]
	v_pk_fma_f32 v[192:193], v[204:205], v[192:193], v[208:209]
	v_pk_fma_f32 v[194:195], v[206:207], v[194:195], v[210:211]
	v_pk_mul_f32 v[192:193], v[192:193], s[82:83] op_sel_hi:[1,0]
	v_pk_mul_f32 v[194:195], v[194:195], s[82:83] op_sel_hi:[1,0]
	v_pk_fma_f32 v[88:89], v[88:89], 0.5, v[192:193] op_sel_hi:[1,0,1]
	v_pk_fma_f32 v[90:91], v[90:91], 0.5, v[194:195] op_sel_hi:[1,0,1]
	s_nop 0
	global_store_dwordx4 v113, v[88:91], s[58:59] offset:64 sc1
	s_nop 1
	global_load_dwordx4 v[192:195], v131, s[60:61] offset:64
	global_load_dwordx4 v[88:91], v133, s[60:61] offset:64
	s_waitcnt vmcnt(10)
	v_pk_add_f32 v[180:181], v[180:181], v[244:245] op_sel_hi:[1,0] neg_lo:[0,1] neg_hi:[0,1]
	v_pk_add_f32 v[182:183], v[182:183], v[244:245] op_sel_hi:[1,0] neg_lo:[0,1] neg_hi:[0,1]
	v_pk_mul_f32 v[180:181], v[180:181], v[244:245] op_sel:[0,1] op_sel_hi:[1,1]
	v_pk_mul_f32 v[182:183], v[182:183], v[244:245] op_sel:[0,1] op_sel_hi:[1,1]
	v_pk_fma_f32 v[180:181], v[196:197], v[180:181], v[200:201]
	v_pk_fma_f32 v[182:183], v[198:199], v[182:183], v[202:203]
	v_pk_mul_f32 v[180:181], v[180:181], s[82:83] op_sel_hi:[1,0]
	v_pk_mul_f32 v[182:183], v[182:183], s[82:83] op_sel_hi:[1,0]
	v_pk_fma_f32 v[122:123], v[122:123], 0.5, v[180:181] op_sel_hi:[1,0,1]
	v_pk_fma_f32 v[124:125], v[124:125], 0.5, v[182:183] op_sel_hi:[1,0,1]
	s_nop 0
	global_store_dwordx4 v130, v[122:125], s[58:59] sc1
	s_nop 1
	global_load_dwordx4 v[122:125], v134, s[60:61]
	s_waitcnt vmcnt(9)
	v_pk_add_f32 v[184:185], v[184:185], v[244:245] op_sel_hi:[1,0] neg_lo:[0,1] neg_hi:[0,1]
	v_pk_add_f32 v[186:187], v[186:187], v[244:245] op_sel_hi:[1,0] neg_lo:[0,1] neg_hi:[0,1]
	v_pk_mul_f32 v[184:185], v[184:185], v[244:245] op_sel:[0,1] op_sel_hi:[1,1]
	v_pk_mul_f32 v[186:187], v[186:187], v[244:245] op_sel:[0,1] op_sel_hi:[1,1]
	v_pk_fma_f32 v[184:185], v[204:205], v[184:185], v[208:209]
	v_pk_fma_f32 v[186:187], v[206:207], v[186:187], v[210:211]
	v_pk_mul_f32 v[184:185], v[184:185], s[82:83] op_sel_hi:[1,0]
	v_pk_mul_f32 v[186:187], v[186:187], s[82:83] op_sel_hi:[1,0]
	v_pk_fma_f32 v[84:85], v[84:85], 0.5, v[184:185] op_sel_hi:[1,0,1]
	v_pk_fma_f32 v[86:87], v[86:87], 0.5, v[186:187] op_sel_hi:[1,0,1]
	s_nop 0
	global_store_dwordx4 v130, v[84:87], s[58:59] offset:64 sc1
	s_nop 1
	global_load_dwordx4 v[84:87], v134, s[60:61] offset:64
	s_waitcnt vmcnt(8)
	v_pk_add_f32 v[188:189], v[188:189], v[246:247] op_sel_hi:[1,0] neg_lo:[0,1] neg_hi:[0,1]
	v_pk_add_f32 v[190:191], v[190:191], v[246:247] op_sel_hi:[1,0] neg_lo:[0,1] neg_hi:[0,1]
	v_pk_mul_f32 v[188:189], v[188:189], v[246:247] op_sel:[0,1] op_sel_hi:[1,1]
	v_pk_mul_f32 v[190:191], v[190:191], v[246:247] op_sel:[0,1] op_sel_hi:[1,1]
	v_pk_fma_f32 v[188:189], v[196:197], v[188:189], v[200:201]
	v_pk_fma_f32 v[190:191], v[198:199], v[190:191], v[202:203]
	v_pk_mul_f32 v[188:189], v[188:189], s[82:83] op_sel_hi:[1,0]
	v_pk_mul_f32 v[190:191], v[190:191], s[82:83] op_sel_hi:[1,0]
	v_pk_fma_f32 v[118:119], v[118:119], 0.5, v[188:189] op_sel_hi:[1,0,1]
	v_pk_fma_f32 v[120:121], v[120:121], 0.5, v[190:191] op_sel_hi:[1,0,1]
	s_nop 0
	global_store_dwordx4 v131, v[118:121], s[58:59] sc1
	s_nop 1
	global_load_dwordx4 v[118:121], v135, s[60:61]
	s_waitcnt vmcnt(7)
	v_pk_add_f32 v[192:193], v[192:193], v[246:247] op_sel_hi:[1,0] neg_lo:[0,1] neg_hi:[0,1]
	v_pk_add_f32 v[194:195], v[194:195], v[246:247] op_sel_hi:[1,0] neg_lo:[0,1] neg_hi:[0,1]
	v_pk_mul_f32 v[192:193], v[192:193], v[246:247] op_sel:[0,1] op_sel_hi:[1,1]
	v_pk_mul_f32 v[194:195], v[194:195], v[246:247] op_sel:[0,1] op_sel_hi:[1,1]
	v_pk_fma_f32 v[192:193], v[204:205], v[192:193], v[208:209]
	v_pk_fma_f32 v[194:195], v[206:207], v[194:195], v[210:211]
	v_pk_mul_f32 v[192:193], v[192:193], s[82:83] op_sel_hi:[1,0]
	v_pk_mul_f32 v[194:195], v[194:195], s[82:83] op_sel_hi:[1,0]
	v_pk_fma_f32 v[80:81], v[80:81], 0.5, v[192:193] op_sel_hi:[1,0,1]
	v_pk_fma_f32 v[82:83], v[82:83], 0.5, v[194:195] op_sel_hi:[1,0,1]
	s_nop 0
	global_store_dwordx4 v131, v[80:83], s[58:59] offset:64 sc1
	s_nop 1
	global_load_dwordx4 v[80:83], v135, s[60:61] offset:64
	v_pk_add_f32 v[138:139], v[138:139], v[248:249] op_sel_hi:[1,0] neg_lo:[0,1] neg_hi:[0,1]
	v_pk_add_f32 v[140:141], v[140:141], v[248:249] op_sel_hi:[1,0] neg_lo:[0,1] neg_hi:[0,1]
	v_pk_mul_f32 v[138:139], v[138:139], v[248:249] op_sel:[0,1] op_sel_hi:[1,1]
	v_pk_mul_f32 v[140:141], v[140:141], v[248:249] op_sel:[0,1] op_sel_hi:[1,1]
	v_pk_fma_f32 v[138:139], v[196:197], v[138:139], v[200:201]
	v_pk_fma_f32 v[140:141], v[198:199], v[140:141], v[202:203]
	v_pk_mul_f32 v[138:139], v[138:139], s[82:83] op_sel_hi:[1,0]
	v_pk_mul_f32 v[140:141], v[140:141], s[82:83] op_sel_hi:[1,0]
	v_pk_fma_f32 v[114:115], v[114:115], 0.5, v[138:139] op_sel_hi:[1,0,1]
	v_pk_fma_f32 v[116:117], v[116:117], 0.5, v[140:141] op_sel_hi:[1,0,1]
	s_nop 0
	global_store_dwordx4 v132, v[114:117], s[58:59] sc1
	s_nop 1
	global_load_dwordx4 v[114:117], v112, s[60:61] offset:512
	v_pk_add_f32 v[92:93], v[92:93], v[248:249] op_sel_hi:[1,0] neg_lo:[0,1] neg_hi:[0,1]
	v_pk_add_f32 v[94:95], v[94:95], v[248:249] op_sel_hi:[1,0] neg_lo:[0,1] neg_hi:[0,1]
	v_pk_mul_f32 v[92:93], v[92:93], v[248:249] op_sel:[0,1] op_sel_hi:[1,1]
	v_pk_mul_f32 v[94:95], v[94:95], v[248:249] op_sel:[0,1] op_sel_hi:[1,1]
	v_pk_fma_f32 v[92:93], v[204:205], v[92:93], v[208:209]
	v_pk_fma_f32 v[94:95], v[206:207], v[94:95], v[210:211]
	v_pk_mul_f32 v[92:93], v[92:93], s[82:83] op_sel_hi:[1,0]
	v_pk_mul_f32 v[94:95], v[94:95], s[82:83] op_sel_hi:[1,0]
	v_pk_fma_f32 v[76:77], v[76:77], 0.5, v[92:93] op_sel_hi:[1,0,1]
	v_pk_fma_f32 v[78:79], v[78:79], 0.5, v[94:95] op_sel_hi:[1,0,1]
	s_nop 0
	global_store_dwordx4 v132, v[76:79], s[58:59] offset:64 sc1
	s_nop 1
	global_load_dwordx4 v[76:79], v112, s[60:61] offset:576
	v_pk_add_f32 v[126:127], v[126:127], v[220:221] op_sel_hi:[1,0] neg_lo:[0,1] neg_hi:[0,1]
	v_pk_add_f32 v[128:129], v[128:129], v[220:221] op_sel_hi:[1,0] neg_lo:[0,1] neg_hi:[0,1]
	v_pk_mul_f32 v[126:127], v[126:127], v[220:221] op_sel:[0,1] op_sel_hi:[1,1]
	v_pk_mul_f32 v[128:129], v[128:129], v[220:221] op_sel:[0,1] op_sel_hi:[1,1]
	v_pk_fma_f32 v[126:127], v[196:197], v[126:127], v[200:201]
	v_pk_fma_f32 v[128:129], v[198:199], v[128:129], v[202:203]
	v_pk_mul_f32 v[126:127], v[126:127], s[82:83] op_sel_hi:[1,0]
	v_pk_mul_f32 v[128:129], v[128:129], s[82:83] op_sel_hi:[1,0]
	v_pk_fma_f32 v[104:105], v[104:105], 0.5, v[126:127] op_sel_hi:[1,0,1]
	v_pk_fma_f32 v[106:107], v[106:107], 0.5, v[128:129] op_sel_hi:[1,0,1]
	s_nop 0
	global_store_dwordx4 v133, v[104:107], s[58:59] sc1
	s_nop 1
	global_load_dwordx4 v[104:107], v113, s[60:61] offset:512
	s_waitcnt vmcnt(14)
	v_pk_add_f32 v[88:89], v[88:89], v[220:221] op_sel_hi:[1,0] neg_lo:[0,1] neg_hi:[0,1]
	v_pk_add_f32 v[90:91], v[90:91], v[220:221] op_sel_hi:[1,0] neg_lo:[0,1] neg_hi:[0,1]
	v_pk_mul_f32 v[88:89], v[88:89], v[220:221] op_sel:[0,1] op_sel_hi:[1,1]
	v_pk_mul_f32 v[90:91], v[90:91], v[220:221] op_sel:[0,1] op_sel_hi:[1,1]
	v_pk_fma_f32 v[88:89], v[204:205], v[88:89], v[208:209]
	v_pk_fma_f32 v[90:91], v[206:207], v[90:91], v[210:211]
	v_pk_mul_f32 v[88:89], v[88:89], s[82:83] op_sel_hi:[1,0]
	v_pk_mul_f32 v[90:91], v[90:91], s[82:83] op_sel_hi:[1,0]
	v_pk_fma_f32 v[72:73], v[72:73], 0.5, v[88:89] op_sel_hi:[1,0,1]
	v_pk_fma_f32 v[74:75], v[74:75], 0.5, v[90:91] op_sel_hi:[1,0,1]
	s_nop 0
	global_store_dwordx4 v133, v[72:75], s[58:59] offset:64 sc1
	s_nop 1
	global_load_dwordx4 v[72:75], v113, s[60:61] offset:576
	s_waitcnt vmcnt(14)
	v_pk_add_f32 v[122:123], v[122:123], v[108:109] op_sel_hi:[1,0] neg_lo:[0,1] neg_hi:[0,1]
	v_pk_add_f32 v[124:125], v[124:125], v[108:109] op_sel_hi:[1,0] neg_lo:[0,1] neg_hi:[0,1]
	v_pk_mul_f32 v[122:123], v[122:123], v[108:109] op_sel:[0,1] op_sel_hi:[1,1]
	v_pk_mul_f32 v[124:125], v[124:125], v[108:109] op_sel:[0,1] op_sel_hi:[1,1]
	v_pk_fma_f32 v[122:123], v[196:197], v[122:123], v[200:201]
	v_pk_fma_f32 v[124:125], v[198:199], v[124:125], v[202:203]
	v_pk_mul_f32 v[122:123], v[122:123], s[82:83] op_sel_hi:[1,0]
	v_pk_mul_f32 v[124:125], v[124:125], s[82:83] op_sel_hi:[1,0]
	v_pk_fma_f32 v[100:101], v[100:101], 0.5, v[122:123] op_sel_hi:[1,0,1]
	v_pk_fma_f32 v[102:103], v[102:103], 0.5, v[124:125] op_sel_hi:[1,0,1]
	s_nop 0
	global_store_dwordx4 v134, v[100:103], s[58:59] sc1
	s_nop 1
	global_load_dwordx4 v[100:103], v130, s[60:61] offset:512
	s_waitcnt vmcnt(14)
	v_pk_add_f32 v[84:85], v[84:85], v[108:109] op_sel_hi:[1,0] neg_lo:[0,1] neg_hi:[0,1]
	v_pk_add_f32 v[86:87], v[86:87], v[108:109] op_sel_hi:[1,0] neg_lo:[0,1] neg_hi:[0,1]
	v_pk_mul_f32 v[84:85], v[84:85], v[108:109] op_sel:[0,1] op_sel_hi:[1,1]
	v_pk_mul_f32 v[86:87], v[86:87], v[108:109] op_sel:[0,1] op_sel_hi:[1,1]
	v_pk_fma_f32 v[84:85], v[204:205], v[84:85], v[208:209]
	v_pk_fma_f32 v[86:87], v[206:207], v[86:87], v[210:211]
	v_pk_mul_f32 v[84:85], v[84:85], s[82:83] op_sel_hi:[1,0]
	v_pk_mul_f32 v[86:87], v[86:87], s[82:83] op_sel_hi:[1,0]
	v_pk_fma_f32 v[68:69], v[68:69], 0.5, v[84:85] op_sel_hi:[1,0,1]
	v_pk_fma_f32 v[70:71], v[70:71], 0.5, v[86:87] op_sel_hi:[1,0,1]
	s_nop 0
	global_store_dwordx4 v134, v[68:71], s[58:59] offset:64 sc1
	s_nop 1
	global_load_dwordx4 v[68:71], v130, s[60:61] offset:576
	s_waitcnt vmcnt(14)
	v_pk_add_f32 v[118:119], v[118:119], v[110:111] op_sel_hi:[1,0] neg_lo:[0,1] neg_hi:[0,1]
	v_pk_add_f32 v[120:121], v[120:121], v[110:111] op_sel_hi:[1,0] neg_lo:[0,1] neg_hi:[0,1]
	v_pk_mul_f32 v[118:119], v[118:119], v[110:111] op_sel:[0,1] op_sel_hi:[1,1]
	v_pk_mul_f32 v[120:121], v[120:121], v[110:111] op_sel:[0,1] op_sel_hi:[1,1]
	v_pk_fma_f32 v[118:119], v[196:197], v[118:119], v[200:201]
	v_pk_fma_f32 v[120:121], v[198:199], v[120:121], v[202:203]
	v_pk_mul_f32 v[118:119], v[118:119], s[82:83] op_sel_hi:[1,0]
	v_pk_mul_f32 v[120:121], v[120:121], s[82:83] op_sel_hi:[1,0]
	v_pk_fma_f32 v[96:97], v[96:97], 0.5, v[118:119] op_sel_hi:[1,0,1]
	v_pk_fma_f32 v[98:99], v[98:99], 0.5, v[120:121] op_sel_hi:[1,0,1]
	s_nop 0
	global_store_dwordx4 v135, v[96:99], s[58:59] sc1
	s_nop 1
	global_load_dwordx4 v[96:99], v131, s[60:61] offset:512
	s_waitcnt vmcnt(14)
	v_pk_add_f32 v[80:81], v[80:81], v[110:111] op_sel_hi:[1,0] neg_lo:[0,1] neg_hi:[0,1]
	v_pk_add_f32 v[82:83], v[82:83], v[110:111] op_sel_hi:[1,0] neg_lo:[0,1] neg_hi:[0,1]
	v_pk_mul_f32 v[80:81], v[80:81], v[110:111] op_sel:[0,1] op_sel_hi:[1,1]
	v_pk_mul_f32 v[82:83], v[82:83], v[110:111] op_sel:[0,1] op_sel_hi:[1,1]
	v_pk_fma_f32 v[80:81], v[204:205], v[80:81], v[208:209]
	v_pk_fma_f32 v[82:83], v[206:207], v[82:83], v[210:211]
	v_pk_mul_f32 v[80:81], v[80:81], s[82:83] op_sel_hi:[1,0]
	v_pk_mul_f32 v[82:83], v[82:83], s[82:83] op_sel_hi:[1,0]
	v_pk_fma_f32 v[64:65], v[64:65], 0.5, v[80:81] op_sel_hi:[1,0,1]
	v_pk_fma_f32 v[66:67], v[66:67], 0.5, v[82:83] op_sel_hi:[1,0,1]
	s_nop 0
	global_store_dwordx4 v135, v[64:67], s[58:59] offset:64 sc1
	s_nop 1
	global_load_dwordx4 v[64:67], v131, s[60:61] offset:576
	s_waitcnt vmcnt(14)
	v_pk_add_f32 v[114:115], v[114:115], v[240:241] op_sel_hi:[1,0] neg_lo:[0,1] neg_hi:[0,1]
	v_pk_add_f32 v[116:117], v[116:117], v[240:241] op_sel_hi:[1,0] neg_lo:[0,1] neg_hi:[0,1]
	v_pk_mul_f32 v[114:115], v[114:115], v[240:241] op_sel:[0,1] op_sel_hi:[1,1]
	v_pk_mul_f32 v[116:117], v[116:117], v[240:241] op_sel:[0,1] op_sel_hi:[1,1]
	v_pk_fma_f32 v[114:115], v[212:213], v[114:115], v[216:217]
	v_pk_fma_f32 v[116:117], v[214:215], v[116:117], v[218:219]
	v_pk_mul_f32 v[114:115], v[114:115], s[82:83] op_sel_hi:[1,0]
	v_pk_mul_f32 v[116:117], v[116:117], s[82:83] op_sel_hi:[1,0]
	v_pk_fma_f32 v[60:61], v[60:61], 0.5, v[114:115] op_sel_hi:[1,0,1]
	v_pk_fma_f32 v[62:63], v[62:63], 0.5, v[116:117] op_sel_hi:[1,0,1]
	s_nop 0
	global_store_dwordx4 v112, v[60:63], s[58:59] offset:512 sc1
	s_nop 1
	global_load_dwordx4 v[60:63], v132, s[60:61] offset:512
	s_waitcnt vmcnt(14)
	v_pk_add_f32 v[76:77], v[76:77], v[240:241] op_sel_hi:[1,0] neg_lo:[0,1] neg_hi:[0,1]
	v_pk_add_f32 v[78:79], v[78:79], v[240:241] op_sel_hi:[1,0] neg_lo:[0,1] neg_hi:[0,1]
	v_pk_mul_f32 v[76:77], v[76:77], v[240:241] op_sel:[0,1] op_sel_hi:[1,1]
	v_pk_mul_f32 v[78:79], v[78:79], v[240:241] op_sel:[0,1] op_sel_hi:[1,1]
	v_pk_fma_f32 v[76:77], v[232:233], v[76:77], v[236:237]
	v_pk_fma_f32 v[78:79], v[234:235], v[78:79], v[238:239]
	v_pk_mul_f32 v[76:77], v[76:77], s[82:83] op_sel_hi:[1,0]
	v_pk_mul_f32 v[78:79], v[78:79], s[82:83] op_sel_hi:[1,0]
	v_pk_fma_f32 v[28:29], v[28:29], 0.5, v[76:77] op_sel_hi:[1,0,1]
	v_pk_fma_f32 v[30:31], v[30:31], 0.5, v[78:79] op_sel_hi:[1,0,1]
	s_nop 0
	global_store_dwordx4 v112, v[28:31], s[58:59] offset:576 sc1
	s_nop 1
	global_load_dwordx4 v[28:31], v132, s[60:61] offset:576
	s_waitcnt vmcnt(14)
	v_pk_add_f32 v[104:105], v[104:105], v[242:243] op_sel_hi:[1,0] neg_lo:[0,1] neg_hi:[0,1]
	v_pk_add_f32 v[106:107], v[106:107], v[242:243] op_sel_hi:[1,0] neg_lo:[0,1] neg_hi:[0,1]
	v_pk_mul_f32 v[104:105], v[104:105], v[242:243] op_sel:[0,1] op_sel_hi:[1,1]
	v_pk_mul_f32 v[106:107], v[106:107], v[242:243] op_sel:[0,1] op_sel_hi:[1,1]
	v_pk_fma_f32 v[104:105], v[212:213], v[104:105], v[216:217]
	v_pk_fma_f32 v[106:107], v[214:215], v[106:107], v[218:219]
	v_pk_mul_f32 v[104:105], v[104:105], s[82:83] op_sel_hi:[1,0]
	v_pk_mul_f32 v[106:107], v[106:107], s[82:83] op_sel_hi:[1,0]
	v_pk_fma_f32 v[56:57], v[56:57], 0.5, v[104:105] op_sel_hi:[1,0,1]
	v_pk_fma_f32 v[58:59], v[58:59], 0.5, v[106:107] op_sel_hi:[1,0,1]
	s_nop 0
	global_store_dwordx4 v113, v[56:59], s[58:59] offset:512 sc1
	s_nop 1
	global_load_dwordx4 v[56:59], v133, s[60:61] offset:512
	s_waitcnt vmcnt(14)
	v_pk_add_f32 v[72:73], v[72:73], v[242:243] op_sel_hi:[1,0] neg_lo:[0,1] neg_hi:[0,1]
	v_pk_add_f32 v[74:75], v[74:75], v[242:243] op_sel_hi:[1,0] neg_lo:[0,1] neg_hi:[0,1]
	v_pk_mul_f32 v[72:73], v[72:73], v[242:243] op_sel:[0,1] op_sel_hi:[1,1]
	v_pk_mul_f32 v[74:75], v[74:75], v[242:243] op_sel:[0,1] op_sel_hi:[1,1]
	v_pk_fma_f32 v[72:73], v[232:233], v[72:73], v[236:237]
	v_pk_fma_f32 v[74:75], v[234:235], v[74:75], v[238:239]
	v_pk_mul_f32 v[72:73], v[72:73], s[82:83] op_sel_hi:[1,0]
	v_pk_mul_f32 v[74:75], v[74:75], s[82:83] op_sel_hi:[1,0]
	v_pk_fma_f32 v[24:25], v[24:25], 0.5, v[72:73] op_sel_hi:[1,0,1]
	v_pk_fma_f32 v[26:27], v[26:27], 0.5, v[74:75] op_sel_hi:[1,0,1]
	s_nop 0
	global_store_dwordx4 v113, v[24:27], s[58:59] offset:576 sc1
	s_nop 1
	global_load_dwordx4 v[24:27], v133, s[60:61] offset:576
	s_waitcnt vmcnt(14)
	v_pk_add_f32 v[100:101], v[100:101], v[244:245] op_sel_hi:[1,0] neg_lo:[0,1] neg_hi:[0,1]
	v_pk_add_f32 v[102:103], v[102:103], v[244:245] op_sel_hi:[1,0] neg_lo:[0,1] neg_hi:[0,1]
	v_pk_mul_f32 v[100:101], v[100:101], v[244:245] op_sel:[0,1] op_sel_hi:[1,1]
	v_pk_mul_f32 v[102:103], v[102:103], v[244:245] op_sel:[0,1] op_sel_hi:[1,1]
	v_pk_fma_f32 v[100:101], v[212:213], v[100:101], v[216:217]
	v_pk_fma_f32 v[102:103], v[214:215], v[102:103], v[218:219]
	v_pk_mul_f32 v[100:101], v[100:101], s[82:83] op_sel_hi:[1,0]
	v_pk_mul_f32 v[102:103], v[102:103], s[82:83] op_sel_hi:[1,0]
	v_pk_fma_f32 v[52:53], v[52:53], 0.5, v[100:101] op_sel_hi:[1,0,1]
	v_pk_fma_f32 v[54:55], v[54:55], 0.5, v[102:103] op_sel_hi:[1,0,1]
	s_nop 0
	global_store_dwordx4 v130, v[52:55], s[58:59] offset:512 sc1
	s_nop 1
	global_load_dwordx4 v[52:55], v134, s[60:61] offset:512
	s_waitcnt vmcnt(14)
	v_pk_add_f32 v[68:69], v[68:69], v[244:245] op_sel_hi:[1,0] neg_lo:[0,1] neg_hi:[0,1]
	v_pk_add_f32 v[70:71], v[70:71], v[244:245] op_sel_hi:[1,0] neg_lo:[0,1] neg_hi:[0,1]
	v_pk_mul_f32 v[68:69], v[68:69], v[244:245] op_sel:[0,1] op_sel_hi:[1,1]
	v_pk_mul_f32 v[70:71], v[70:71], v[244:245] op_sel:[0,1] op_sel_hi:[1,1]
	v_pk_fma_f32 v[68:69], v[232:233], v[68:69], v[236:237]
	v_pk_fma_f32 v[70:71], v[234:235], v[70:71], v[238:239]
	v_pk_mul_f32 v[68:69], v[68:69], s[82:83] op_sel_hi:[1,0]
	v_pk_mul_f32 v[70:71], v[70:71], s[82:83] op_sel_hi:[1,0]
	v_pk_fma_f32 v[20:21], v[20:21], 0.5, v[68:69] op_sel_hi:[1,0,1]
	v_pk_fma_f32 v[22:23], v[22:23], 0.5, v[70:71] op_sel_hi:[1,0,1]
	s_nop 0
	global_store_dwordx4 v130, v[20:23], s[58:59] offset:576 sc1
	s_nop 1
	global_load_dwordx4 v[20:23], v134, s[60:61] offset:576
	s_waitcnt vmcnt(14)
	v_pk_add_f32 v[96:97], v[96:97], v[246:247] op_sel_hi:[1,0] neg_lo:[0,1] neg_hi:[0,1]
	v_pk_add_f32 v[98:99], v[98:99], v[246:247] op_sel_hi:[1,0] neg_lo:[0,1] neg_hi:[0,1]
	v_pk_mul_f32 v[96:97], v[96:97], v[246:247] op_sel:[0,1] op_sel_hi:[1,1]
	v_pk_mul_f32 v[98:99], v[98:99], v[246:247] op_sel:[0,1] op_sel_hi:[1,1]
	v_pk_fma_f32 v[96:97], v[212:213], v[96:97], v[216:217]
	v_pk_fma_f32 v[98:99], v[214:215], v[98:99], v[218:219]
	v_pk_mul_f32 v[96:97], v[96:97], s[82:83] op_sel_hi:[1,0]
	v_pk_mul_f32 v[98:99], v[98:99], s[82:83] op_sel_hi:[1,0]
	v_pk_fma_f32 v[48:49], v[48:49], 0.5, v[96:97] op_sel_hi:[1,0,1]
	v_pk_fma_f32 v[50:51], v[50:51], 0.5, v[98:99] op_sel_hi:[1,0,1]
	s_nop 0
	global_store_dwordx4 v131, v[48:51], s[58:59] offset:512 sc1
	s_nop 1
	global_load_dwordx4 v[48:51], v135, s[60:61] offset:512
	s_waitcnt vmcnt(14)
	v_pk_add_f32 v[64:65], v[64:65], v[246:247] op_sel_hi:[1,0] neg_lo:[0,1] neg_hi:[0,1]
	v_pk_add_f32 v[66:67], v[66:67], v[246:247] op_sel_hi:[1,0] neg_lo:[0,1] neg_hi:[0,1]
	v_pk_mul_f32 v[64:65], v[64:65], v[246:247] op_sel:[0,1] op_sel_hi:[1,1]
	v_pk_mul_f32 v[66:67], v[66:67], v[246:247] op_sel:[0,1] op_sel_hi:[1,1]
	v_pk_fma_f32 v[64:65], v[232:233], v[64:65], v[236:237]
	v_pk_fma_f32 v[66:67], v[234:235], v[66:67], v[238:239]
	v_pk_mul_f32 v[64:65], v[64:65], s[82:83] op_sel_hi:[1,0]
	v_pk_mul_f32 v[66:67], v[66:67], s[82:83] op_sel_hi:[1,0]
	v_pk_fma_f32 v[16:17], v[16:17], 0.5, v[64:65] op_sel_hi:[1,0,1]
	v_pk_fma_f32 v[18:19], v[18:19], 0.5, v[66:67] op_sel_hi:[1,0,1]
	s_nop 0
	global_store_dwordx4 v131, v[16:19], s[58:59] offset:576 sc1
	s_nop 1
	global_load_dwordx4 v[16:19], v135, s[60:61] offset:576
	s_waitcnt vmcnt(14)
	v_pk_add_f32 v[60:61], v[60:61], v[248:249] op_sel_hi:[1,0] neg_lo:[0,1] neg_hi:[0,1]
	v_pk_add_f32 v[62:63], v[62:63], v[248:249] op_sel_hi:[1,0] neg_lo:[0,1] neg_hi:[0,1]
	v_pk_mul_f32 v[60:61], v[60:61], v[248:249] op_sel:[0,1] op_sel_hi:[1,1]
	v_pk_mul_f32 v[62:63], v[62:63], v[248:249] op_sel:[0,1] op_sel_hi:[1,1]
	v_pk_fma_f32 v[60:61], v[212:213], v[60:61], v[216:217]
	v_pk_fma_f32 v[62:63], v[214:215], v[62:63], v[218:219]
	v_pk_mul_f32 v[60:61], v[60:61], s[82:83] op_sel_hi:[1,0]
	v_pk_mul_f32 v[62:63], v[62:63], s[82:83] op_sel_hi:[1,0]
	v_pk_fma_f32 v[44:45], v[44:45], 0.5, v[60:61] op_sel_hi:[1,0,1]
	v_pk_fma_f32 v[46:47], v[46:47], 0.5, v[62:63] op_sel_hi:[1,0,1]
	s_nop 0
	global_store_dwordx4 v132, v[44:47], s[58:59] offset:512 sc1
	s_nop 1
	s_waitcnt vmcnt(13)
	v_pk_add_f32 v[28:29], v[28:29], v[248:249] op_sel_hi:[1,0] neg_lo:[0,1] neg_hi:[0,1]
	v_pk_add_f32 v[30:31], v[30:31], v[248:249] op_sel_hi:[1,0] neg_lo:[0,1] neg_hi:[0,1]
	v_pk_mul_f32 v[28:29], v[28:29], v[248:249] op_sel:[0,1] op_sel_hi:[1,1]
	v_pk_mul_f32 v[30:31], v[30:31], v[248:249] op_sel:[0,1] op_sel_hi:[1,1]
	v_pk_fma_f32 v[28:29], v[232:233], v[28:29], v[236:237]
	v_pk_fma_f32 v[30:31], v[234:235], v[30:31], v[238:239]
	v_pk_mul_f32 v[28:29], v[28:29], s[82:83] op_sel_hi:[1,0]
	v_pk_mul_f32 v[30:31], v[30:31], s[82:83] op_sel_hi:[1,0]
	v_pk_fma_f32 v[12:13], v[12:13], 0.5, v[28:29] op_sel_hi:[1,0,1]
	v_pk_fma_f32 v[14:15], v[14:15], 0.5, v[30:31] op_sel_hi:[1,0,1]
	s_nop 0
	global_store_dwordx4 v132, v[12:15], s[58:59] offset:576 sc1
	s_nop 1
	s_waitcnt vmcnt(12)
	v_pk_add_f32 v[56:57], v[56:57], v[220:221] op_sel_hi:[1,0] neg_lo:[0,1] neg_hi:[0,1]
	v_pk_add_f32 v[58:59], v[58:59], v[220:221] op_sel_hi:[1,0] neg_lo:[0,1] neg_hi:[0,1]
	v_pk_mul_f32 v[56:57], v[56:57], v[220:221] op_sel:[0,1] op_sel_hi:[1,1]
	v_pk_mul_f32 v[58:59], v[58:59], v[220:221] op_sel:[0,1] op_sel_hi:[1,1]
	v_pk_fma_f32 v[56:57], v[212:213], v[56:57], v[216:217]
	v_pk_fma_f32 v[58:59], v[214:215], v[58:59], v[218:219]
	v_pk_mul_f32 v[56:57], v[56:57], s[82:83] op_sel_hi:[1,0]
	v_pk_mul_f32 v[58:59], v[58:59], s[82:83] op_sel_hi:[1,0]
	v_pk_fma_f32 v[40:41], v[40:41], 0.5, v[56:57] op_sel_hi:[1,0,1]
	v_pk_fma_f32 v[42:43], v[42:43], 0.5, v[58:59] op_sel_hi:[1,0,1]
	s_nop 0
	global_store_dwordx4 v133, v[40:43], s[58:59] offset:512 sc1
	s_nop 1
	s_waitcnt vmcnt(11)
	v_pk_add_f32 v[24:25], v[24:25], v[220:221] op_sel_hi:[1,0] neg_lo:[0,1] neg_hi:[0,1]
	v_pk_add_f32 v[26:27], v[26:27], v[220:221] op_sel_hi:[1,0] neg_lo:[0,1] neg_hi:[0,1]
	v_pk_mul_f32 v[24:25], v[24:25], v[220:221] op_sel:[0,1] op_sel_hi:[1,1]
	v_pk_mul_f32 v[26:27], v[26:27], v[220:221] op_sel:[0,1] op_sel_hi:[1,1]
	v_pk_fma_f32 v[24:25], v[232:233], v[24:25], v[236:237]
	v_pk_fma_f32 v[26:27], v[234:235], v[26:27], v[238:239]
	v_pk_mul_f32 v[24:25], v[24:25], s[82:83] op_sel_hi:[1,0]
	v_pk_mul_f32 v[26:27], v[26:27], s[82:83] op_sel_hi:[1,0]
	v_pk_fma_f32 v[8:9], v[8:9], 0.5, v[24:25] op_sel_hi:[1,0,1]
	v_pk_fma_f32 v[10:11], v[10:11], 0.5, v[26:27] op_sel_hi:[1,0,1]
	s_nop 0
	global_store_dwordx4 v133, v[8:11], s[58:59] offset:576 sc1
	s_nop 1
	s_waitcnt vmcnt(10)
	v_pk_add_f32 v[52:53], v[52:53], v[108:109] op_sel_hi:[1,0] neg_lo:[0,1] neg_hi:[0,1]
	v_pk_add_f32 v[54:55], v[54:55], v[108:109] op_sel_hi:[1,0] neg_lo:[0,1] neg_hi:[0,1]
	v_pk_mul_f32 v[52:53], v[52:53], v[108:109] op_sel:[0,1] op_sel_hi:[1,1]
	v_pk_mul_f32 v[54:55], v[54:55], v[108:109] op_sel:[0,1] op_sel_hi:[1,1]
	v_pk_fma_f32 v[52:53], v[212:213], v[52:53], v[216:217]
	v_pk_fma_f32 v[54:55], v[214:215], v[54:55], v[218:219]
	v_pk_mul_f32 v[52:53], v[52:53], s[82:83] op_sel_hi:[1,0]
	v_pk_mul_f32 v[54:55], v[54:55], s[82:83] op_sel_hi:[1,0]
	v_pk_fma_f32 v[36:37], v[36:37], 0.5, v[52:53] op_sel_hi:[1,0,1]
	v_pk_fma_f32 v[38:39], v[38:39], 0.5, v[54:55] op_sel_hi:[1,0,1]
	s_nop 0
	global_store_dwordx4 v134, v[36:39], s[58:59] offset:512 sc1
	s_nop 1
	s_waitcnt vmcnt(9)
	v_pk_add_f32 v[20:21], v[20:21], v[108:109] op_sel_hi:[1,0] neg_lo:[0,1] neg_hi:[0,1]
	v_pk_add_f32 v[22:23], v[22:23], v[108:109] op_sel_hi:[1,0] neg_lo:[0,1] neg_hi:[0,1]
	v_pk_mul_f32 v[20:21], v[20:21], v[108:109] op_sel:[0,1] op_sel_hi:[1,1]
	v_pk_mul_f32 v[22:23], v[22:23], v[108:109] op_sel:[0,1] op_sel_hi:[1,1]
	v_pk_fma_f32 v[20:21], v[232:233], v[20:21], v[236:237]
	v_pk_fma_f32 v[22:23], v[234:235], v[22:23], v[238:239]
	v_pk_mul_f32 v[20:21], v[20:21], s[82:83] op_sel_hi:[1,0]
	v_pk_mul_f32 v[22:23], v[22:23], s[82:83] op_sel_hi:[1,0]
	v_pk_fma_f32 v[4:5], v[4:5], 0.5, v[20:21] op_sel_hi:[1,0,1]
	v_pk_fma_f32 v[6:7], v[6:7], 0.5, v[22:23] op_sel_hi:[1,0,1]
	s_nop 0
	global_store_dwordx4 v134, v[4:7], s[58:59] offset:576 sc1
	s_nop 1
	s_waitcnt vmcnt(8)
	v_pk_add_f32 v[48:49], v[48:49], v[110:111] op_sel_hi:[1,0] neg_lo:[0,1] neg_hi:[0,1]
	v_pk_add_f32 v[50:51], v[50:51], v[110:111] op_sel_hi:[1,0] neg_lo:[0,1] neg_hi:[0,1]
	v_pk_mul_f32 v[48:49], v[48:49], v[110:111] op_sel:[0,1] op_sel_hi:[1,1]
	v_pk_mul_f32 v[50:51], v[50:51], v[110:111] op_sel:[0,1] op_sel_hi:[1,1]
	v_pk_fma_f32 v[48:49], v[212:213], v[48:49], v[216:217]
	v_pk_fma_f32 v[50:51], v[214:215], v[50:51], v[218:219]
	v_pk_mul_f32 v[48:49], v[48:49], s[82:83] op_sel_hi:[1,0]
	v_pk_mul_f32 v[50:51], v[50:51], s[82:83] op_sel_hi:[1,0]
	v_pk_fma_f32 v[32:33], v[32:33], 0.5, v[48:49] op_sel_hi:[1,0,1]
	v_pk_fma_f32 v[34:35], v[34:35], 0.5, v[50:51] op_sel_hi:[1,0,1]
	s_nop 0
	global_store_dwordx4 v135, v[32:35], s[58:59] offset:512 sc1
	s_nop 1
	s_waitcnt vmcnt(7)
	v_pk_add_f32 v[16:17], v[16:17], v[110:111] op_sel_hi:[1,0] neg_lo:[0,1] neg_hi:[0,1]
	v_pk_add_f32 v[18:19], v[18:19], v[110:111] op_sel_hi:[1,0] neg_lo:[0,1] neg_hi:[0,1]
	v_pk_mul_f32 v[16:17], v[16:17], v[110:111] op_sel:[0,1] op_sel_hi:[1,1]
	v_pk_mul_f32 v[18:19], v[18:19], v[110:111] op_sel:[0,1] op_sel_hi:[1,1]
	v_pk_fma_f32 v[16:17], v[232:233], v[16:17], v[236:237]
	v_pk_fma_f32 v[18:19], v[234:235], v[18:19], v[238:239]
	v_pk_mul_f32 v[16:17], v[16:17], s[82:83] op_sel_hi:[1,0]
	v_pk_mul_f32 v[18:19], v[18:19], s[82:83] op_sel_hi:[1,0]
	v_pk_fma_f32 v[0:1], v[0:1], 0.5, v[16:17] op_sel_hi:[1,0,1]
	v_pk_fma_f32 v[2:3], v[2:3], 0.5, v[18:19] op_sel_hi:[1,0,1]
	s_nop 0
	global_store_dwordx4 v135, v[0:3], s[58:59] offset:576 sc1
	s_nop 1
	s_branch .Lepi_A_join
.Lepi_A_nostats:
	s_mov_b64 s[40:41], exec
	v_lshl_add_u32 v112, v160, 2, v137
	v_lshl_add_u32 v113, v164, 2, v137
	v_lshl_add_u32 v130, v166, 2, v137
	v_lshl_add_u32 v131, v168, 2, v137
	v_lshl_add_u32 v132, v162, 2, v137
	v_lshl_add_u32 v133, v170, 2, v137
	v_lshl_add_u32 v134, v172, 2, v137
	v_lshl_add_u32 v135, v174, 2, v137
	global_load_dwordx4 v[180:183], v112, s[60:61]
	global_load_dwordx4 v[184:187], v112, s[60:61] offset:64
	global_load_dwordx4 v[188:191], v113, s[60:61]
	global_load_dwordx4 v[192:195], v113, s[60:61] offset:64
	s_waitcnt vmcnt(3)
	v_pk_mul_f32 v[180:181], v[180:181], s[82:83] op_sel_hi:[1,0]
	v_pk_mul_f32 v[182:183], v[182:183], s[82:83] op_sel_hi:[1,0]
	v_pk_fma_f32 v[138:139], v[138:139], 0.5, v[180:181] op_sel_hi:[1,0,1]
	v_pk_fma_f32 v[140:141], v[140:141], 0.5, v[182:183] op_sel_hi:[1,0,1]
	s_nop 0
	global_store_dwordx4 v112, v[138:141], s[58:59] sc1
	s_nop 1
	global_load_dwordx4 v[180:183], v130, s[60:61]
	global_load_dwordx4 v[138:141], v132, s[60:61]
	s_waitcnt vmcnt(5)
	v_pk_mul_f32 v[184:185], v[184:185], s[82:83] op_sel_hi:[1,0]
	v_pk_mul_f32 v[186:187], v[186:187], s[82:83] op_sel_hi:[1,0]
	v_pk_fma_f32 v[92:93], v[92:93], 0.5, v[184:185] op_sel_hi:[1,0,1]
	v_pk_fma_f32 v[94:95], v[94:95], 0.5, v[186:187] op_sel_hi:[1,0,1]
	s_nop 0
	global_store_dwordx4 v112, v[92:95], s[58:59] offset:64 sc1
	s_nop 1
	global_load_dwordx4 v[184:187], v130, s[60:61] offset:64
	global_load_dwordx4 v[92:95], v132, s[60:61] offset:64
	s_waitcnt vmcnt(7)
	v_pk_mul_f32 v[188:189], v[188:189], s[82:83] op_sel_hi:[1,0]
	v_pk_mul_f32 v[190:191], v[190:191], s[82:83] op_sel_hi:[1,0]
	v_pk_fma_f32 v[126:127], v[126:127], 0.5, v[188:189] op_sel_hi:[1,0,1]
	v_pk_fma_f32 v[128:129], v[128:129], 0.5, v[190:191] op_sel_hi:[1,0,1]
	s_nop 0
	global_store_dwordx4 v113, v[126:129], s[58:59] sc1
	s_nop 1
	global_load_dwordx4 v[188:191], v131, s[60:61]
	global_load_dwordx4 v[126:129], v133, s[60:61]
	s_waitcnt vmcnt(9)
	v_pk_mul_f32 v[192:193], v[192:193], s[82:83] op_sel_hi:[1,0]
	v_pk_mul_f32 v[194:195], v[194:195], s[82:83] op_sel_hi:[1,0]
	v_pk_fma_f32 v[88:89], v[88:89], 0.5, v[192:193] op_sel_hi:[1,0,1]
	v_pk_fma_f32 v[90:91], v[90:91], 0.5, v[194:195] op_sel_hi:[1,0,1]
	s_nop 0
	global_store_dwordx4 v113, v[88:91], s[58:59] offset:64 sc1
	s_nop 1
	global_load_dwordx4 v[192:195], v131, s[60:61] offset:64
	global_load_dwordx4 v[88:91], v133, s[60:61] offset:64
	s_waitcnt vmcnt(10)
	v_pk_mul_f32 v[180:181], v[180:181], s[82:83] op_sel_hi:[1,0]
	v_pk_mul_f32 v[182:183], v[182:183], s[82:83] op_sel_hi:[1,0]
	v_pk_fma_f32 v[122:123], v[122:123], 0.5, v[180:181] op_sel_hi:[1,0,1]
	v_pk_fma_f32 v[124:125], v[124:125], 0.5, v[182:183] op_sel_hi:[1,0,1]
	s_nop 0
	global_store_dwordx4 v130, v[122:125], s[58:59] sc1
	s_nop 1
	global_load_dwordx4 v[122:125], v134, s[60:61]
	s_waitcnt vmcnt(9)
	v_pk_mul_f32 v[184:185], v[184:185], s[82:83] op_sel_hi:[1,0]
	v_pk_mul_f32 v[186:187], v[186:187], s[82:83] op_sel_hi:[1,0]
	v_pk_fma_f32 v[84:85], v[84:85], 0.5, v[184:185] op_sel_hi:[1,0,1]
	v_pk_fma_f32 v[86:87], v[86:87], 0.5, v[186:187] op_sel_hi:[1,0,1]
	s_nop 0
	global_store_dwordx4 v130, v[84:87], s[58:59] offset:64 sc1
	s_nop 1
	global_load_dwordx4 v[84:87], v134, s[60:61] offset:64
	s_waitcnt vmcnt(8)
	v_pk_mul_f32 v[188:189], v[188:189], s[82:83] op_sel_hi:[1,0]
	v_pk_mul_f32 v[190:191], v[190:191], s[82:83] op_sel_hi:[1,0]
	v_pk_fma_f32 v[118:119], v[118:119], 0.5, v[188:189] op_sel_hi:[1,0,1]
	v_pk_fma_f32 v[120:121], v[120:121], 0.5, v[190:191] op_sel_hi:[1,0,1]
	s_nop 0
	global_store_dwordx4 v131, v[118:121], s[58:59] sc1
	s_nop 1
	global_load_dwordx4 v[118:121], v135, s[60:61]
	s_waitcnt vmcnt(7)
	v_pk_mul_f32 v[192:193], v[192:193], s[82:83] op_sel_hi:[1,0]
	v_pk_mul_f32 v[194:195], v[194:195], s[82:83] op_sel_hi:[1,0]
	v_pk_fma_f32 v[80:81], v[80:81], 0.5, v[192:193] op_sel_hi:[1,0,1]
	v_pk_fma_f32 v[82:83], v[82:83], 0.5, v[194:195] op_sel_hi:[1,0,1]
	s_nop 0
	global_store_dwordx4 v131, v[80:83], s[58:59] offset:64 sc1
	s_nop 1
	global_load_dwordx4 v[80:83], v135, s[60:61] offset:64
	v_pk_mul_f32 v[138:139], v[138:139], s[82:83] op_sel_hi:[1,0]
	v_pk_mul_f32 v[140:141], v[140:141], s[82:83] op_sel_hi:[1,0]
	v_pk_fma_f32 v[114:115], v[114:115], 0.5, v[138:139] op_sel_hi:[1,0,1]
	v_pk_fma_f32 v[116:117], v[116:117], 0.5, v[140:141] op_sel_hi:[1,0,1]
	s_nop 0
	global_store_dwordx4 v132, v[114:117], s[58:59] sc1
	s_nop 1
	global_load_dwordx4 v[114:117], v112, s[60:61] offset:512
	v_pk_mul_f32 v[92:93], v[92:93], s[82:83] op_sel_hi:[1,0]
	v_pk_mul_f32 v[94:95], v[94:95], s[82:83] op_sel_hi:[1,0]
	v_pk_fma_f32 v[76:77], v[76:77], 0.5, v[92:93] op_sel_hi:[1,0,1]
	v_pk_fma_f32 v[78:79], v[78:79], 0.5, v[94:95] op_sel_hi:[1,0,1]
	s_nop 0
	global_store_dwordx4 v132, v[76:79], s[58:59] offset:64 sc1
	s_nop 1
	global_load_dwordx4 v[76:79], v112, s[60:61] offset:576
	v_pk_mul_f32 v[126:127], v[126:127], s[82:83] op_sel_hi:[1,0]
	v_pk_mul_f32 v[128:129], v[128:129], s[82:83] op_sel_hi:[1,0]
	v_pk_fma_f32 v[104:105], v[104:105], 0.5, v[126:127] op_sel_hi:[1,0,1]
	v_pk_fma_f32 v[106:107], v[106:107], 0.5, v[128:129] op_sel_hi:[1,0,1]
	s_nop 0
	global_store_dwordx4 v133, v[104:107], s[58:59] sc1
	s_nop 1
	global_load_dwordx4 v[104:107], v113, s[60:61] offset:512
	s_waitcnt vmcnt(14)
	v_pk_mul_f32 v[88:89], v[88:89], s[82:83] op_sel_hi:[1,0]
	v_pk_mul_f32 v[90:91], v[90:91], s[82:83] op_sel_hi:[1,0]
	v_pk_fma_f32 v[72:73], v[72:73], 0.5, v[88:89] op_sel_hi:[1,0,1]
	v_pk_fma_f32 v[74:75], v[74:75], 0.5, v[90:91] op_sel_hi:[1,0,1]
	s_nop 0
	global_store_dwordx4 v133, v[72:75], s[58:59] offset:64 sc1
	s_nop 1
	global_load_dwordx4 v[72:75], v113, s[60:61] offset:576
	s_waitcnt vmcnt(14)
	v_pk_mul_f32 v[122:123], v[122:123], s[82:83] op_sel_hi:[1,0]
	v_pk_mul_f32 v[124:125], v[124:125], s[82:83] op_sel_hi:[1,0]
	v_pk_fma_f32 v[100:101], v[100:101], 0.5, v[122:123] op_sel_hi:[1,0,1]
	v_pk_fma_f32 v[102:103], v[102:103], 0.5, v[124:125] op_sel_hi:[1,0,1]
	s_nop 0
	global_store_dwordx4 v134, v[100:103], s[58:59] sc1
	s_nop 1
	global_load_dwordx4 v[100:103], v130, s[60:61] offset:512
	s_waitcnt vmcnt(14)
	v_pk_mul_f32 v[84:85], v[84:85], s[82:83] op_sel_hi:[1,0]
	v_pk_mul_f32 v[86:87], v[86:87], s[82:83] op_sel_hi:[1,0]
	v_pk_fma_f32 v[68:69], v[68:69], 0.5, v[84:85] op_sel_hi:[1,0,1]
	v_pk_fma_f32 v[70:71], v[70:71], 0.5, v[86:87] op_sel_hi:[1,0,1]
	s_nop 0
	global_store_dwordx4 v134, v[68:71], s[58:59] offset:64 sc1
	s_nop 1
	global_load_dwordx4 v[68:71], v130, s[60:61] offset:576
	s_waitcnt vmcnt(14)
	v_pk_mul_f32 v[118:119], v[118:119], s[82:83] op_sel_hi:[1,0]
	v_pk_mul_f32 v[120:121], v[120:121], s[82:83] op_sel_hi:[1,0]
	v_pk_fma_f32 v[96:97], v[96:97], 0.5, v[118:119] op_sel_hi:[1,0,1]
	v_pk_fma_f32 v[98:99], v[98:99], 0.5, v[120:121] op_sel_hi:[1,0,1]
	s_nop 0
	global_store_dwordx4 v135, v[96:99], s[58:59] sc1
	s_nop 1
	global_load_dwordx4 v[96:99], v131, s[60:61] offset:512
	s_waitcnt vmcnt(14)
	v_pk_mul_f32 v[80:81], v[80:81], s[82:83] op_sel_hi:[1,0]
	v_pk_mul_f32 v[82:83], v[82:83], s[82:83] op_sel_hi:[1,0]
	v_pk_fma_f32 v[64:65], v[64:65], 0.5, v[80:81] op_sel_hi:[1,0,1]
	v_pk_fma_f32 v[66:67], v[66:67], 0.5, v[82:83] op_sel_hi:[1,0,1]
	s_nop 0
	global_store_dwordx4 v135, v[64:67], s[58:59] offset:64 sc1
	s_nop 1
	global_load_dwordx4 v[64:67], v131, s[60:61] offset:576
	s_waitcnt vmcnt(14)
	v_pk_mul_f32 v[114:115], v[114:115], s[82:83] op_sel_hi:[1,0]
	v_pk_mul_f32 v[116:117], v[116:117], s[82:83] op_sel_hi:[1,0]
	v_pk_fma_f32 v[60:61], v[60:61], 0.5, v[114:115] op_sel_hi:[1,0,1]
	v_pk_fma_f32 v[62:63], v[62:63], 0.5, v[116:117] op_sel_hi:[1,0,1]
	s_nop 0
	global_store_dwordx4 v112, v[60:63], s[58:59] offset:512 sc1
	s_nop 1
	global_load_dwordx4 v[60:63], v132, s[60:61] offset:512
	s_waitcnt vmcnt(14)
	v_pk_mul_f32 v[76:77], v[76:77], s[82:83] op_sel_hi:[1,0]
	v_pk_mul_f32 v[78:79], v[78:79], s[82:83] op_sel_hi:[1,0]
	v_pk_fma_f32 v[28:29], v[28:29], 0.5, v[76:77] op_sel_hi:[1,0,1]
	v_pk_fma_f32 v[30:31], v[30:31], 0.5, v[78:79] op_sel_hi:[1,0,1]
	s_nop 0
	global_store_dwordx4 v112, v[28:31], s[58:59] offset:576 sc1
	s_nop 1
	global_load_dwordx4 v[28:31], v132, s[60:61] offset:576
	s_waitcnt vmcnt(14)
	v_pk_mul_f32 v[104:105], v[104:105], s[82:83] op_sel_hi:[1,0]
	v_pk_mul_f32 v[106:107], v[106:107], s[82:83] op_sel_hi:[1,0]
	v_pk_fma_f32 v[56:57], v[56:57], 0.5, v[104:105] op_sel_hi:[1,0,1]
	v_pk_fma_f32 v[58:59], v[58:59], 0.5, v[106:107] op_sel_hi:[1,0,1]
	s_nop 0
	global_store_dwordx4 v113, v[56:59], s[58:59] offset:512 sc1
	s_nop 1
	global_load_dwordx4 v[56:59], v133, s[60:61] offset:512
	s_waitcnt vmcnt(14)
	v_pk_mul_f32 v[72:73], v[72:73], s[82:83] op_sel_hi:[1,0]
	v_pk_mul_f32 v[74:75], v[74:75], s[82:83] op_sel_hi:[1,0]
	v_pk_fma_f32 v[24:25], v[24:25], 0.5, v[72:73] op_sel_hi:[1,0,1]
	v_pk_fma_f32 v[26:27], v[26:27], 0.5, v[74:75] op_sel_hi:[1,0,1]
	s_nop 0
	global_store_dwordx4 v113, v[24:27], s[58:59] offset:576 sc1
	s_nop 1
	global_load_dwordx4 v[24:27], v133, s[60:61] offset:576
	s_waitcnt vmcnt(14)
	v_pk_mul_f32 v[100:101], v[100:101], s[82:83] op_sel_hi:[1,0]
	v_pk_mul_f32 v[102:103], v[102:103], s[82:83] op_sel_hi:[1,0]
	v_pk_fma_f32 v[52:53], v[52:53], 0.5, v[100:101] op_sel_hi:[1,0,1]
	v_pk_fma_f32 v[54:55], v[54:55], 0.5, v[102:103] op_sel_hi:[1,0,1]
	s_nop 0
	global_store_dwordx4 v130, v[52:55], s[58:59] offset:512 sc1
	s_nop 1
	global_load_dwordx4 v[52:55], v134, s[60:61] offset:512
	s_waitcnt vmcnt(14)
	v_pk_mul_f32 v[68:69], v[68:69], s[82:83] op_sel_hi:[1,0]
	v_pk_mul_f32 v[70:71], v[70:71], s[82:83] op_sel_hi:[1,0]
	v_pk_fma_f32 v[20:21], v[20:21], 0.5, v[68:69] op_sel_hi:[1,0,1]
	v_pk_fma_f32 v[22:23], v[22:23], 0.5, v[70:71] op_sel_hi:[1,0,1]
	s_nop 0
	global_store_dwordx4 v130, v[20:23], s[58:59] offset:576 sc1
	s_nop 1
	global_load_dwordx4 v[20:23], v134, s[60:61] offset:576
	s_waitcnt vmcnt(14)
	v_pk_mul_f32 v[96:97], v[96:97], s[82:83] op_sel_hi:[1,0]
	v_pk_mul_f32 v[98:99], v[98:99], s[82:83] op_sel_hi:[1,0]
	v_pk_fma_f32 v[48:49], v[48:49], 0.5, v[96:97] op_sel_hi:[1,0,1]
	v_pk_fma_f32 v[50:51], v[50:51], 0.5, v[98:99] op_sel_hi:[1,0,1]
	s_nop 0
	global_store_dwordx4 v131, v[48:51], s[58:59] offset:512 sc1
	s_nop 1
	global_load_dwordx4 v[48:51], v135, s[60:61] offset:512
	s_waitcnt vmcnt(14)
	v_pk_mul_f32 v[64:65], v[64:65], s[82:83] op_sel_hi:[1,0]
	v_pk_mul_f32 v[66:67], v[66:67], s[82:83] op_sel_hi:[1,0]
	v_pk_fma_f32 v[16:17], v[16:17], 0.5, v[64:65] op_sel_hi:[1,0,1]
	v_pk_fma_f32 v[18:19], v[18:19], 0.5, v[66:67] op_sel_hi:[1,0,1]
	s_nop 0
	global_store_dwordx4 v131, v[16:19], s[58:59] offset:576 sc1
	s_nop 1
	global_load_dwordx4 v[16:19], v135, s[60:61] offset:576
	s_waitcnt vmcnt(14)
	v_pk_mul_f32 v[60:61], v[60:61], s[82:83] op_sel_hi:[1,0]
	v_pk_mul_f32 v[62:63], v[62:63], s[82:83] op_sel_hi:[1,0]
	v_pk_fma_f32 v[44:45], v[44:45], 0.5, v[60:61] op_sel_hi:[1,0,1]
	v_pk_fma_f32 v[46:47], v[46:47], 0.5, v[62:63] op_sel_hi:[1,0,1]
	s_nop 0
	global_store_dwordx4 v132, v[44:47], s[58:59] offset:512 sc1
	s_nop 1
	s_waitcnt vmcnt(13)
	v_pk_mul_f32 v[28:29], v[28:29], s[82:83] op_sel_hi:[1,0]
	v_pk_mul_f32 v[30:31], v[30:31], s[82:83] op_sel_hi:[1,0]
	v_pk_fma_f32 v[12:13], v[12:13], 0.5, v[28:29] op_sel_hi:[1,0,1]
	v_pk_fma_f32 v[14:15], v[14:15], 0.5, v[30:31] op_sel_hi:[1,0,1]
	s_nop 0
	global_store_dwordx4 v132, v[12:15], s[58:59] offset:576 sc1
	s_nop 1
	s_waitcnt vmcnt(12)
	v_pk_mul_f32 v[56:57], v[56:57], s[82:83] op_sel_hi:[1,0]
	v_pk_mul_f32 v[58:59], v[58:59], s[82:83] op_sel_hi:[1,0]
	v_pk_fma_f32 v[40:41], v[40:41], 0.5, v[56:57] op_sel_hi:[1,0,1]
	v_pk_fma_f32 v[42:43], v[42:43], 0.5, v[58:59] op_sel_hi:[1,0,1]
	s_nop 0
	global_store_dwordx4 v133, v[40:43], s[58:59] offset:512 sc1
	s_nop 1
	s_waitcnt vmcnt(11)
	v_pk_mul_f32 v[24:25], v[24:25], s[82:83] op_sel_hi:[1,0]
	v_pk_mul_f32 v[26:27], v[26:27], s[82:83] op_sel_hi:[1,0]
	v_pk_fma_f32 v[8:9], v[8:9], 0.5, v[24:25] op_sel_hi:[1,0,1]
	v_pk_fma_f32 v[10:11], v[10:11], 0.5, v[26:27] op_sel_hi:[1,0,1]
	s_nop 0
	global_store_dwordx4 v133, v[8:11], s[58:59] offset:576 sc1
	s_nop 1
	s_waitcnt vmcnt(10)
	v_pk_mul_f32 v[52:53], v[52:53], s[82:83] op_sel_hi:[1,0]
	v_pk_mul_f32 v[54:55], v[54:55], s[82:83] op_sel_hi:[1,0]
	v_pk_fma_f32 v[36:37], v[36:37], 0.5, v[52:53] op_sel_hi:[1,0,1]
	v_pk_fma_f32 v[38:39], v[38:39], 0.5, v[54:55] op_sel_hi:[1,0,1]
	s_nop 0
	global_store_dwordx4 v134, v[36:39], s[58:59] offset:512 sc1
	s_nop 1
	s_waitcnt vmcnt(9)
	v_pk_mul_f32 v[20:21], v[20:21], s[82:83] op_sel_hi:[1,0]
	v_pk_mul_f32 v[22:23], v[22:23], s[82:83] op_sel_hi:[1,0]
	v_pk_fma_f32 v[4:5], v[4:5], 0.5, v[20:21] op_sel_hi:[1,0,1]
	v_pk_fma_f32 v[6:7], v[6:7], 0.5, v[22:23] op_sel_hi:[1,0,1]
	s_nop 0
	global_store_dwordx4 v134, v[4:7], s[58:59] offset:576 sc1
	s_nop 1
	s_waitcnt vmcnt(8)
	v_pk_mul_f32 v[48:49], v[48:49], s[82:83] op_sel_hi:[1,0]
	v_pk_mul_f32 v[50:51], v[50:51], s[82:83] op_sel_hi:[1,0]
	v_pk_fma_f32 v[32:33], v[32:33], 0.5, v[48:49] op_sel_hi:[1,0,1]
	v_pk_fma_f32 v[34:35], v[34:35], 0.5, v[50:51] op_sel_hi:[1,0,1]
	s_nop 0
	global_store_dwordx4 v135, v[32:35], s[58:59] offset:512 sc1
	s_nop 1
	s_waitcnt vmcnt(7)
	v_pk_mul_f32 v[16:17], v[16:17], s[82:83] op_sel_hi:[1,0]
	v_pk_mul_f32 v[18:19], v[18:19], s[82:83] op_sel_hi:[1,0]
	v_pk_fma_f32 v[0:1], v[0:1], 0.5, v[16:17] op_sel_hi:[1,0,1]
	v_pk_fma_f32 v[2:3], v[2:3], 0.5, v[18:19] op_sel_hi:[1,0,1]
	s_nop 0
	global_store_dwordx4 v135, v[0:3], s[58:59] offset:576 sc1
	s_nop 1

.LBB0_1086:
	v_lshl_add_u32 v248, s60, 8, v138
	v_lshl_or_b32 v249, s75, 8, v139
	v_lshlrev_b32_e32 v248, 3, v248
	v_lshlrev_b32_e32 v249, 2, v249
	s_ashr_i32 s61, s60, 31
	s_lshl_b64 s[28:29], s[60:61], 20
	v_readlane_b32 s4, v252, 0
	v_readlane_b32 s5, v252, 1
	v_readlane_b32 s6, v252, 2
	v_readlane_b32 s7, v252, 3
	v_readlane_b32 s8, v252, 4
	v_readlane_b32 s9, v252, 5
	v_readlane_b32 s10, v252, 6
	v_readlane_b32 s11, v252, 7
	v_readlane_b32 s12, v252, 8
	v_readlane_b32 s13, v252, 9
	v_readlane_b32 s14, v252, 10
	v_readlane_b32 s15, v252, 11
	v_readlane_b32 s16, v252, 12
	v_readlane_b32 s17, v252, 13
	s_mov_b64 s[4:5], s[8:9]
	v_readlane_b32 s18, v252, 14
	v_readlane_b32 s19, v252, 15
	s_mov_b64 s[6:7], s[10:11]
	s_mov_b64 s[8:9], s[12:13]
	s_mov_b64 s[12:13], s[16:17]
	s_add_u32 s60, s12, s28
	s_addc_u32 s61, s13, s29
	s_mov_b64 s[14:15], s[18:19]
	global_load_dwordx2 v[208:209], v248, s[92:93]
	global_load_dwordx2 v[210:211], v248, s[92:93] offset:128
	global_load_dwordx2 v[212:213], v248, s[92:93] offset:256
	global_load_dwordx2 v[214:215], v248, s[92:93] offset:384
	global_load_dwordx2 v[216:217], v248, s[92:93] offset:1024
	global_load_dwordx2 v[218:219], v248, s[92:93] offset:1152
	global_load_dwordx2 v[220:221], v248, s[92:93] offset:1280
	global_load_dwordx2 v[230:231], v248, s[92:93] offset:1408
	global_load_dwordx4 v[190:193], v249, s[44:45]
	global_load_dwordx4 v[194:197], v249, s[46:47]
	global_load_dwordx4 v[200:203], v249, s[44:45] offset:64
	global_load_dwordx4 v[204:207], v249, s[46:47] offset:64
	global_load_dwordx4 v[232:235], v249, s[44:45] offset:512
	global_load_dwordx4 v[236:239], v249, s[46:47] offset:512
	global_load_dwordx4 v[240:243], v249, s[44:45] offset:576
	global_load_dwordx4 v[244:247], v249, s[46:47] offset:576
	v_add_u32_e32 v124, v140, v249
	v_add_u32_e32 v125, v164, v249
	v_add_u32_e32 v126, v166, v249
	v_add_u32_e32 v127, v168, v249
	v_add_u32_e32 v128, v156, v249
	v_add_u32_e32 v129, v158, v249
	v_add_u32_e32 v130, v160, v249
	v_add_u32_e32 v131, v162, v249
	global_load_dwordx4 v[174:177], v124, s[60:61]
	global_load_dwordx4 v[178:181], v124, s[60:61] offset:64
	global_load_dwordx4 v[182:185], v125, s[60:61]
	global_load_dwordx4 v[186:189], v125, s[60:61] offset:64
	s_waitcnt vmcnt(3)
	v_pk_add_f32 v[174:175], v[174:175], v[208:209] op_sel_hi:[1,0] neg_lo:[0,1] neg_hi:[0,1]
	v_pk_add_f32 v[176:177], v[176:177], v[208:209] op_sel_hi:[1,0] neg_lo:[0,1] neg_hi:[0,1]
	v_pk_mul_f32 v[174:175], v[174:175], v[208:209] op_sel:[0,1] op_sel_hi:[1,1]
	v_pk_mul_f32 v[176:177], v[176:177], v[208:209] op_sel:[0,1] op_sel_hi:[1,1]
	v_pk_fma_f32 v[174:175], v[190:191], v[174:175], v[194:195]
	v_pk_fma_f32 v[176:177], v[192:193], v[176:177], v[196:197]
	v_pk_fma_f32 v[132:133], v[174:175], s[82:83], v[132:133] op_sel_hi:[1,0,1]
	v_pk_fma_f32 v[134:135], v[176:177], s[82:83], v[134:135] op_sel_hi:[1,0,1]
	s_nop 0
	global_store_dwordx4 v124, v[132:135], s[60:61] sc1
	s_nop 1
	global_load_dwordx4 v[174:177], v126, s[60:61]
	global_load_dwordx4 v[132:135], v128, s[60:61]
	s_waitcnt vmcnt(5)
	v_pk_add_f32 v[178:179], v[178:179], v[208:209] op_sel_hi:[1,0] neg_lo:[0,1] neg_hi:[0,1]
	v_pk_add_f32 v[180:181], v[180:181], v[208:209] op_sel_hi:[1,0] neg_lo:[0,1] neg_hi:[0,1]
	v_pk_mul_f32 v[178:179], v[178:179], v[208:209] op_sel:[0,1] op_sel_hi:[1,1]
	v_pk_mul_f32 v[180:181], v[180:181], v[208:209] op_sel:[0,1] op_sel_hi:[1,1]
	v_pk_fma_f32 v[178:179], v[200:201], v[178:179], v[204:205]
	v_pk_fma_f32 v[180:181], v[202:203], v[180:181], v[206:207]
	v_pk_fma_f32 v[96:97], v[178:179], s[82:83], v[96:97] op_sel_hi:[1,0,1]
	v_pk_fma_f32 v[98:99], v[180:181], s[82:83], v[98:99] op_sel_hi:[1,0,1]
	s_nop 0
	global_store_dwordx4 v124, v[96:99], s[60:61] offset:64 sc1
	s_nop 1
	global_load_dwordx4 v[178:181], v126, s[60:61] offset:64
	global_load_dwordx4 v[96:99], v128, s[60:61] offset:64
	s_waitcnt vmcnt(7)
	v_pk_add_f32 v[182:183], v[182:183], v[210:211] op_sel_hi:[1,0] neg_lo:[0,1] neg_hi:[0,1]
	v_pk_add_f32 v[184:185], v[184:185], v[210:211] op_sel_hi:[1,0] neg_lo:[0,1] neg_hi:[0,1]
	v_pk_mul_f32 v[182:183], v[182:183], v[210:211] op_sel:[0,1] op_sel_hi:[1,1]
	v_pk_mul_f32 v[184:185], v[184:185], v[210:211] op_sel:[0,1] op_sel_hi:[1,1]
	v_pk_fma_f32 v[182:183], v[190:191], v[182:183], v[194:195]
	v_pk_fma_f32 v[184:185], v[192:193], v[184:185], v[196:197]
	v_pk_fma_f32 v[120:121], v[182:183], s[82:83], v[120:121] op_sel_hi:[1,0,1]
	v_pk_fma_f32 v[122:123], v[184:185], s[82:83], v[122:123] op_sel_hi:[1,0,1]
	s_nop 0
	global_store_dwordx4 v125, v[120:123], s[60:61] sc1
	s_nop 1
	global_load_dwordx4 v[182:185], v127, s[60:61]
	global_load_dwordx4 v[120:123], v129, s[60:61]
	s_waitcnt vmcnt(9)
	v_pk_add_f32 v[186:187], v[186:187], v[210:211] op_sel_hi:[1,0] neg_lo:[0,1] neg_hi:[0,1]
	v_pk_add_f32 v[188:189], v[188:189], v[210:211] op_sel_hi:[1,0] neg_lo:[0,1] neg_hi:[0,1]
	v_pk_mul_f32 v[186:187], v[186:187], v[210:211] op_sel:[0,1] op_sel_hi:[1,1]
	v_pk_mul_f32 v[188:189], v[188:189], v[210:211] op_sel:[0,1] op_sel_hi:[1,1]
	v_pk_fma_f32 v[186:187], v[200:201], v[186:187], v[204:205]
	v_pk_fma_f32 v[188:189], v[202:203], v[188:189], v[206:207]
	v_pk_fma_f32 v[88:89], v[186:187], s[82:83], v[88:89] op_sel_hi:[1,0,1]
	v_pk_fma_f32 v[90:91], v[188:189], s[82:83], v[90:91] op_sel_hi:[1,0,1]
	s_nop 0
	global_store_dwordx4 v125, v[88:91], s[60:61] offset:64 sc1
	s_nop 1
	global_load_dwordx4 v[186:189], v127, s[60:61] offset:64
	global_load_dwordx4 v[88:91], v129, s[60:61] offset:64
	s_waitcnt vmcnt(10)
	v_pk_add_f32 v[174:175], v[174:175], v[212:213] op_sel_hi:[1,0] neg_lo:[0,1] neg_hi:[0,1]
	v_pk_add_f32 v[176:177], v[176:177], v[212:213] op_sel_hi:[1,0] neg_lo:[0,1] neg_hi:[0,1]
	v_pk_mul_f32 v[174:175], v[174:175], v[212:213] op_sel:[0,1] op_sel_hi:[1,1]
	v_pk_mul_f32 v[176:177], v[176:177], v[212:213] op_sel:[0,1] op_sel_hi:[1,1]
	v_pk_fma_f32 v[174:175], v[190:191], v[174:175], v[194:195]
	v_pk_fma_f32 v[176:177], v[192:193], v[176:177], v[196:197]
	v_pk_fma_f32 v[116:117], v[174:175], s[82:83], v[116:117] op_sel_hi:[1,0,1]
	v_pk_fma_f32 v[118:119], v[176:177], s[82:83], v[118:119] op_sel_hi:[1,0,1]
	s_nop 0
	global_store_dwordx4 v126, v[116:119], s[60:61] sc1
	s_nop 1
	global_load_dwordx4 v[116:119], v130, s[60:61]
	s_waitcnt vmcnt(9)
	v_pk_add_f32 v[178:179], v[178:179], v[212:213] op_sel_hi:[1,0] neg_lo:[0,1] neg_hi:[0,1]
	v_pk_add_f32 v[180:181], v[180:181], v[212:213] op_sel_hi:[1,0] neg_lo:[0,1] neg_hi:[0,1]
	v_pk_mul_f32 v[178:179], v[178:179], v[212:213] op_sel:[0,1] op_sel_hi:[1,1]
	v_pk_mul_f32 v[180:181], v[180:181], v[212:213] op_sel:[0,1] op_sel_hi:[1,1]
	v_pk_fma_f32 v[178:179], v[200:201], v[178:179], v[204:205]
	v_pk_fma_f32 v[180:181], v[202:203], v[180:181], v[206:207]
	v_pk_fma_f32 v[84:85], v[178:179], s[82:83], v[84:85] op_sel_hi:[1,0,1]
	v_pk_fma_f32 v[86:87], v[180:181], s[82:83], v[86:87] op_sel_hi:[1,0,1]
	s_nop 0
	global_store_dwordx4 v126, v[84:87], s[60:61] offset:64 sc1
	s_nop 1
	global_load_dwordx4 v[84:87], v130, s[60:61] offset:64
	s_waitcnt vmcnt(8)
	v_pk_add_f32 v[182:183], v[182:183], v[214:215] op_sel_hi:[1,0] neg_lo:[0,1] neg_hi:[0,1]
	v_pk_add_f32 v[184:185], v[184:185], v[214:215] op_sel_hi:[1,0] neg_lo:[0,1] neg_hi:[0,1]
	v_pk_mul_f32 v[182:183], v[182:183], v[214:215] op_sel:[0,1] op_sel_hi:[1,1]
	v_pk_mul_f32 v[184:185], v[184:185], v[214:215] op_sel:[0,1] op_sel_hi:[1,1]
	v_pk_fma_f32 v[182:183], v[190:191], v[182:183], v[194:195]
	v_pk_fma_f32 v[184:185], v[192:193], v[184:185], v[196:197]
	v_pk_fma_f32 v[112:113], v[182:183], s[82:83], v[112:113] op_sel_hi:[1,0,1]
	v_pk_fma_f32 v[114:115], v[184:185], s[82:83], v[114:115] op_sel_hi:[1,0,1]
	s_nop 0
	global_store_dwordx4 v127, v[112:115], s[60:61] sc1
	s_nop 1
	global_load_dwordx4 v[112:115], v131, s[60:61]
	s_waitcnt vmcnt(7)
	v_pk_add_f32 v[186:187], v[186:187], v[214:215] op_sel_hi:[1,0] neg_lo:[0,1] neg_hi:[0,1]
	v_pk_add_f32 v[188:189], v[188:189], v[214:215] op_sel_hi:[1,0] neg_lo:[0,1] neg_hi:[0,1]
	v_pk_mul_f32 v[186:187], v[186:187], v[214:215] op_sel:[0,1] op_sel_hi:[1,1]
	v_pk_mul_f32 v[188:189], v[188:189], v[214:215] op_sel:[0,1] op_sel_hi:[1,1]
	v_pk_fma_f32 v[186:187], v[200:201], v[186:187], v[204:205]
	v_pk_fma_f32 v[188:189], v[202:203], v[188:189], v[206:207]
	v_pk_fma_f32 v[80:81], v[186:187], s[82:83], v[80:81] op_sel_hi:[1,0,1]
	v_pk_fma_f32 v[82:83], v[188:189], s[82:83], v[82:83] op_sel_hi:[1,0,1]
	s_nop 0
	global_store_dwordx4 v127, v[80:83], s[60:61] offset:64 sc1
	s_nop 1
	global_load_dwordx4 v[80:83], v131, s[60:61] offset:64
	v_pk_add_f32 v[132:133], v[132:133], v[216:217] op_sel_hi:[1,0] neg_lo:[0,1] neg_hi:[0,1]
	v_pk_add_f32 v[134:135], v[134:135], v[216:217] op_sel_hi:[1,0] neg_lo:[0,1] neg_hi:[0,1]
	v_pk_mul_f32 v[132:133], v[132:133], v[216:217] op_sel:[0,1] op_sel_hi:[1,1]
	v_pk_mul_f32 v[134:135], v[134:135], v[216:217] op_sel:[0,1] op_sel_hi:[1,1]
	v_pk_fma_f32 v[132:133], v[190:191], v[132:133], v[194:195]
	v_pk_fma_f32 v[134:135], v[192:193], v[134:135], v[196:197]
	v_pk_fma_f32 v[108:109], v[132:133], s[82:83], v[108:109] op_sel_hi:[1,0,1]
	v_pk_fma_f32 v[110:111], v[134:135], s[82:83], v[110:111] op_sel_hi:[1,0,1]
	s_nop 0
	global_store_dwordx4 v128, v[108:111], s[60:61] sc1
	s_nop 1
	global_load_dwordx4 v[108:111], v124, s[60:61] offset:512
	v_pk_add_f32 v[96:97], v[96:97], v[216:217] op_sel_hi:[1,0] neg_lo:[0,1] neg_hi:[0,1]
	v_pk_add_f32 v[98:99], v[98:99], v[216:217] op_sel_hi:[1,0] neg_lo:[0,1] neg_hi:[0,1]
	v_pk_mul_f32 v[96:97], v[96:97], v[216:217] op_sel:[0,1] op_sel_hi:[1,1]
	v_pk_mul_f32 v[98:99], v[98:99], v[216:217] op_sel:[0,1] op_sel_hi:[1,1]
	v_pk_fma_f32 v[96:97], v[200:201], v[96:97], v[204:205]
	v_pk_fma_f32 v[98:99], v[202:203], v[98:99], v[206:207]
	v_pk_fma_f32 v[76:77], v[96:97], s[82:83], v[76:77] op_sel_hi:[1,0,1]
	v_pk_fma_f32 v[78:79], v[98:99], s[82:83], v[78:79] op_sel_hi:[1,0,1]
	s_nop 0
	global_store_dwordx4 v128, v[76:79], s[60:61] offset:64 sc1
	s_nop 1
	global_load_dwordx4 v[76:79], v124, s[60:61] offset:576
	v_pk_add_f32 v[120:121], v[120:121], v[218:219] op_sel_hi:[1,0] neg_lo:[0,1] neg_hi:[0,1]
	v_pk_add_f32 v[122:123], v[122:123], v[218:219] op_sel_hi:[1,0] neg_lo:[0,1] neg_hi:[0,1]
	v_pk_mul_f32 v[120:121], v[120:121], v[218:219] op_sel:[0,1] op_sel_hi:[1,1]
	v_pk_mul_f32 v[122:123], v[122:123], v[218:219] op_sel:[0,1] op_sel_hi:[1,1]
	v_pk_fma_f32 v[120:121], v[190:191], v[120:121], v[194:195]
	v_pk_fma_f32 v[122:123], v[192:193], v[122:123], v[196:197]
	v_pk_fma_f32 v[104:105], v[120:121], s[82:83], v[104:105] op_sel_hi:[1,0,1]
	v_pk_fma_f32 v[106:107], v[122:123], s[82:83], v[106:107] op_sel_hi:[1,0,1]
	s_nop 0
	global_store_dwordx4 v129, v[104:107], s[60:61] sc1
	s_nop 1
	global_load_dwordx4 v[104:107], v125, s[60:61] offset:512
	s_waitcnt vmcnt(14)
	v_pk_add_f32 v[88:89], v[88:89], v[218:219] op_sel_hi:[1,0] neg_lo:[0,1] neg_hi:[0,1]
	v_pk_add_f32 v[90:91], v[90:91], v[218:219] op_sel_hi:[1,0] neg_lo:[0,1] neg_hi:[0,1]
	v_pk_mul_f32 v[88:89], v[88:89], v[218:219] op_sel:[0,1] op_sel_hi:[1,1]
	v_pk_mul_f32 v[90:91], v[90:91], v[218:219] op_sel:[0,1] op_sel_hi:[1,1]
	v_pk_fma_f32 v[88:89], v[200:201], v[88:89], v[204:205]
	v_pk_fma_f32 v[90:91], v[202:203], v[90:91], v[206:207]
	v_pk_fma_f32 v[72:73], v[88:89], s[82:83], v[72:73] op_sel_hi:[1,0,1]
	v_pk_fma_f32 v[74:75], v[90:91], s[82:83], v[74:75] op_sel_hi:[1,0,1]
	s_nop 0
	global_store_dwordx4 v129, v[72:75], s[60:61] offset:64 sc1
	s_nop 1
	global_load_dwordx4 v[72:75], v125, s[60:61] offset:576
	s_waitcnt vmcnt(14)
	v_pk_add_f32 v[116:117], v[116:117], v[220:221] op_sel_hi:[1,0] neg_lo:[0,1] neg_hi:[0,1]
	v_pk_add_f32 v[118:119], v[118:119], v[220:221] op_sel_hi:[1,0] neg_lo:[0,1] neg_hi:[0,1]
	v_pk_mul_f32 v[116:117], v[116:117], v[220:221] op_sel:[0,1] op_sel_hi:[1,1]
	v_pk_mul_f32 v[118:119], v[118:119], v[220:221] op_sel:[0,1] op_sel_hi:[1,1]
	v_pk_fma_f32 v[116:117], v[190:191], v[116:117], v[194:195]
	v_pk_fma_f32 v[118:119], v[192:193], v[118:119], v[196:197]
	v_pk_fma_f32 v[100:101], v[116:117], s[82:83], v[100:101] op_sel_hi:[1,0,1]
	v_pk_fma_f32 v[102:103], v[118:119], s[82:83], v[102:103] op_sel_hi:[1,0,1]
	s_nop 0
	global_store_dwordx4 v130, v[100:103], s[60:61] sc1
	s_nop 1
	global_load_dwordx4 v[100:103], v126, s[60:61] offset:512
	s_waitcnt vmcnt(14)
	v_pk_add_f32 v[84:85], v[84:85], v[220:221] op_sel_hi:[1,0] neg_lo:[0,1] neg_hi:[0,1]
	v_pk_add_f32 v[86:87], v[86:87], v[220:221] op_sel_hi:[1,0] neg_lo:[0,1] neg_hi:[0,1]
	v_pk_mul_f32 v[84:85], v[84:85], v[220:221] op_sel:[0,1] op_sel_hi:[1,1]
	v_pk_mul_f32 v[86:87], v[86:87], v[220:221] op_sel:[0,1] op_sel_hi:[1,1]
	v_pk_fma_f32 v[84:85], v[200:201], v[84:85], v[204:205]
	v_pk_fma_f32 v[86:87], v[202:203], v[86:87], v[206:207]
	v_pk_fma_f32 v[68:69], v[84:85], s[82:83], v[68:69] op_sel_hi:[1,0,1]
	v_pk_fma_f32 v[70:71], v[86:87], s[82:83], v[70:71] op_sel_hi:[1,0,1]
	s_nop 0
	global_store_dwordx4 v130, v[68:71], s[60:61] offset:64 sc1
	s_nop 1
	global_load_dwordx4 v[68:71], v126, s[60:61] offset:576
	s_waitcnt vmcnt(14)
	v_pk_add_f32 v[112:113], v[112:113], v[230:231] op_sel_hi:[1,0] neg_lo:[0,1] neg_hi:[0,1]
	v_pk_add_f32 v[114:115], v[114:115], v[230:231] op_sel_hi:[1,0] neg_lo:[0,1] neg_hi:[0,1]
	v_pk_mul_f32 v[112:113], v[112:113], v[230:231] op_sel:[0,1] op_sel_hi:[1,1]
	v_pk_mul_f32 v[114:115], v[114:115], v[230:231] op_sel:[0,1] op_sel_hi:[1,1]
	v_pk_fma_f32 v[112:113], v[190:191], v[112:113], v[194:195]
	v_pk_fma_f32 v[114:115], v[192:193], v[114:115], v[196:197]
	v_pk_fma_f32 v[92:93], v[112:113], s[82:83], v[92:93] op_sel_hi:[1,0,1]
	v_pk_fma_f32 v[94:95], v[114:115], s[82:83], v[94:95] op_sel_hi:[1,0,1]
	s_nop 0
	global_store_dwordx4 v131, v[92:95], s[60:61] sc1
	s_nop 1
	global_load_dwordx4 v[92:95], v127, s[60:61] offset:512
	s_waitcnt vmcnt(14)
	v_pk_add_f32 v[80:81], v[80:81], v[230:231] op_sel_hi:[1,0] neg_lo:[0,1] neg_hi:[0,1]
	v_pk_add_f32 v[82:83], v[82:83], v[230:231] op_sel_hi:[1,0] neg_lo:[0,1] neg_hi:[0,1]
	v_pk_mul_f32 v[80:81], v[80:81], v[230:231] op_sel:[0,1] op_sel_hi:[1,1]
	v_pk_mul_f32 v[82:83], v[82:83], v[230:231] op_sel:[0,1] op_sel_hi:[1,1]
	v_pk_fma_f32 v[80:81], v[200:201], v[80:81], v[204:205]
	v_pk_fma_f32 v[82:83], v[202:203], v[82:83], v[206:207]
	v_pk_fma_f32 v[60:61], v[80:81], s[82:83], v[60:61] op_sel_hi:[1,0,1]
	v_pk_fma_f32 v[62:63], v[82:83], s[82:83], v[62:63] op_sel_hi:[1,0,1]
	s_nop 0
	global_store_dwordx4 v131, v[60:63], s[60:61] offset:64 sc1
	s_nop 1
	global_load_dwordx4 v[60:63], v127, s[60:61] offset:576
	s_waitcnt vmcnt(14)
	v_pk_add_f32 v[108:109], v[108:109], v[208:209] op_sel_hi:[1,0] neg_lo:[0,1] neg_hi:[0,1]
	v_pk_add_f32 v[110:111], v[110:111], v[208:209] op_sel_hi:[1,0] neg_lo:[0,1] neg_hi:[0,1]
	v_pk_mul_f32 v[108:109], v[108:109], v[208:209] op_sel:[0,1] op_sel_hi:[1,1]
	v_pk_mul_f32 v[110:111], v[110:111], v[208:209] op_sel:[0,1] op_sel_hi:[1,1]
	v_pk_fma_f32 v[108:109], v[232:233], v[108:109], v[236:237]
	v_pk_fma_f32 v[110:111], v[234:235], v[110:111], v[238:239]
	v_pk_fma_f32 v[64:65], v[108:109], s[82:83], v[64:65] op_sel_hi:[1,0,1]
	v_pk_fma_f32 v[66:67], v[110:111], s[82:83], v[66:67] op_sel_hi:[1,0,1]
	s_nop 0
	global_store_dwordx4 v124, v[64:67], s[60:61] offset:512 sc1
	s_nop 1
	global_load_dwordx4 v[64:67], v128, s[60:61] offset:512
	s_waitcnt vmcnt(14)
	v_pk_add_f32 v[76:77], v[76:77], v[208:209] op_sel_hi:[1,0] neg_lo:[0,1] neg_hi:[0,1]
	v_pk_add_f32 v[78:79], v[78:79], v[208:209] op_sel_hi:[1,0] neg_lo:[0,1] neg_hi:[0,1]
	v_pk_mul_f32 v[76:77], v[76:77], v[208:209] op_sel:[0,1] op_sel_hi:[1,1]
	v_pk_mul_f32 v[78:79], v[78:79], v[208:209] op_sel:[0,1] op_sel_hi:[1,1]
	v_pk_fma_f32 v[76:77], v[240:241], v[76:77], v[244:245]
	v_pk_fma_f32 v[78:79], v[242:243], v[78:79], v[246:247]
	v_pk_fma_f32 v[32:33], v[76:77], s[82:83], v[32:33] op_sel_hi:[1,0,1]
	v_pk_fma_f32 v[34:35], v[78:79], s[82:83], v[34:35] op_sel_hi:[1,0,1]
	s_nop 0
	global_store_dwordx4 v124, v[32:35], s[60:61] offset:576 sc1
	s_nop 1
	global_load_dwordx4 v[32:35], v128, s[60:61] offset:576
	s_waitcnt vmcnt(14)
	v_pk_add_f32 v[104:105], v[104:105], v[210:211] op_sel_hi:[1,0] neg_lo:[0,1] neg_hi:[0,1]
	v_pk_add_f32 v[106:107], v[106:107], v[210:211] op_sel_hi:[1,0] neg_lo:[0,1] neg_hi:[0,1]
	v_pk_mul_f32 v[104:105], v[104:105], v[210:211] op_sel:[0,1] op_sel_hi:[1,1]
	v_pk_mul_f32 v[106:107], v[106:107], v[210:211] op_sel:[0,1] op_sel_hi:[1,1]
	v_pk_fma_f32 v[104:105], v[232:233], v[104:105], v[236:237]
	v_pk_fma_f32 v[106:107], v[234:235], v[106:107], v[238:239]
	v_pk_fma_f32 v[56:57], v[104:105], s[82:83], v[56:57] op_sel_hi:[1,0,1]
	v_pk_fma_f32 v[58:59], v[106:107], s[82:83], v[58:59] op_sel_hi:[1,0,1]
	s_nop 0
	global_store_dwordx4 v125, v[56:59], s[60:61] offset:512 sc1
	s_nop 1
	global_load_dwordx4 v[56:59], v129, s[60:61] offset:512
	s_waitcnt vmcnt(14)
	v_pk_add_f32 v[72:73], v[72:73], v[210:211] op_sel_hi:[1,0] neg_lo:[0,1] neg_hi:[0,1]
	v_pk_add_f32 v[74:75], v[74:75], v[210:211] op_sel_hi:[1,0] neg_lo:[0,1] neg_hi:[0,1]
	v_pk_mul_f32 v[72:73], v[72:73], v[210:211] op_sel:[0,1] op_sel_hi:[1,1]
	v_pk_mul_f32 v[74:75], v[74:75], v[210:211] op_sel:[0,1] op_sel_hi:[1,1]
	v_pk_fma_f32 v[72:73], v[240:241], v[72:73], v[244:245]
	v_pk_fma_f32 v[74:75], v[242:243], v[74:75], v[246:247]
	v_pk_fma_f32 v[24:25], v[72:73], s[82:83], v[24:25] op_sel_hi:[1,0,1]
	v_pk_fma_f32 v[26:27], v[74:75], s[82:83], v[26:27] op_sel_hi:[1,0,1]
	s_nop 0
	global_store_dwordx4 v125, v[24:27], s[60:61] offset:576 sc1
	s_nop 1
	global_load_dwordx4 v[24:27], v129, s[60:61] offset:576
	s_waitcnt vmcnt(14)
	v_pk_add_f32 v[100:101], v[100:101], v[212:213] op_sel_hi:[1,0] neg_lo:[0,1] neg_hi:[0,1]
	v_pk_add_f32 v[102:103], v[102:103], v[212:213] op_sel_hi:[1,0] neg_lo:[0,1] neg_hi:[0,1]
	v_pk_mul_f32 v[100:101], v[100:101], v[212:213] op_sel:[0,1] op_sel_hi:[1,1]
	v_pk_mul_f32 v[102:103], v[102:103], v[212:213] op_sel:[0,1] op_sel_hi:[1,1]
	v_pk_fma_f32 v[100:101], v[232:233], v[100:101], v[236:237]
	v_pk_fma_f32 v[102:103], v[234:235], v[102:103], v[238:239]
	v_pk_fma_f32 v[52:53], v[100:101], s[82:83], v[52:53] op_sel_hi:[1,0,1]
	v_pk_fma_f32 v[54:55], v[102:103], s[82:83], v[54:55] op_sel_hi:[1,0,1]
	s_nop 0
	global_store_dwordx4 v126, v[52:55], s[60:61] offset:512 sc1
	s_nop 1
	global_load_dwordx4 v[52:55], v130, s[60:61] offset:512
	s_waitcnt vmcnt(14)
	v_pk_add_f32 v[68:69], v[68:69], v[212:213] op_sel_hi:[1,0] neg_lo:[0,1] neg_hi:[0,1]
	v_pk_add_f32 v[70:71], v[70:71], v[212:213] op_sel_hi:[1,0] neg_lo:[0,1] neg_hi:[0,1]
	v_pk_mul_f32 v[68:69], v[68:69], v[212:213] op_sel:[0,1] op_sel_hi:[1,1]
	v_pk_mul_f32 v[70:71], v[70:71], v[212:213] op_sel:[0,1] op_sel_hi:[1,1]
	v_pk_fma_f32 v[68:69], v[240:241], v[68:69], v[244:245]
	v_pk_fma_f32 v[70:71], v[242:243], v[70:71], v[246:247]
	v_pk_fma_f32 v[20:21], v[68:69], s[82:83], v[20:21] op_sel_hi:[1,0,1]
	v_pk_fma_f32 v[22:23], v[70:71], s[82:83], v[22:23] op_sel_hi:[1,0,1]
	s_nop 0
	global_store_dwordx4 v126, v[20:23], s[60:61] offset:576 sc1
	s_nop 1
	global_load_dwordx4 v[20:23], v130, s[60:61] offset:576
	s_waitcnt vmcnt(14)
	v_pk_add_f32 v[92:93], v[92:93], v[214:215] op_sel_hi:[1,0] neg_lo:[0,1] neg_hi:[0,1]
	v_pk_add_f32 v[94:95], v[94:95], v[214:215] op_sel_hi:[1,0] neg_lo:[0,1] neg_hi:[0,1]
	v_pk_mul_f32 v[92:93], v[92:93], v[214:215] op_sel:[0,1] op_sel_hi:[1,1]
	v_pk_mul_f32 v[94:95], v[94:95], v[214:215] op_sel:[0,1] op_sel_hi:[1,1]
	v_pk_fma_f32 v[92:93], v[232:233], v[92:93], v[236:237]
	v_pk_fma_f32 v[94:95], v[234:235], v[94:95], v[238:239]
	v_pk_fma_f32 v[48:49], v[92:93], s[82:83], v[48:49] op_sel_hi:[1,0,1]
	v_pk_fma_f32 v[50:51], v[94:95], s[82:83], v[50:51] op_sel_hi:[1,0,1]
	s_nop 0
	global_store_dwordx4 v127, v[48:51], s[60:61] offset:512 sc1
	s_nop 1
	global_load_dwordx4 v[48:51], v131, s[60:61] offset:512
	s_waitcnt vmcnt(14)
	v_pk_add_f32 v[60:61], v[60:61], v[214:215] op_sel_hi:[1,0] neg_lo:[0,1] neg_hi:[0,1]
	v_pk_add_f32 v[62:63], v[62:63], v[214:215] op_sel_hi:[1,0] neg_lo:[0,1] neg_hi:[0,1]
	v_pk_mul_f32 v[60:61], v[60:61], v[214:215] op_sel:[0,1] op_sel_hi:[1,1]
	v_pk_mul_f32 v[62:63], v[62:63], v[214:215] op_sel:[0,1] op_sel_hi:[1,1]
	v_pk_fma_f32 v[60:61], v[240:241], v[60:61], v[244:245]
	v_pk_fma_f32 v[62:63], v[242:243], v[62:63], v[246:247]
	v_pk_fma_f32 v[16:17], v[60:61], s[82:83], v[16:17] op_sel_hi:[1,0,1]
	v_pk_fma_f32 v[18:19], v[62:63], s[82:83], v[18:19] op_sel_hi:[1,0,1]
	s_nop 0
	global_store_dwordx4 v127, v[16:19], s[60:61] offset:576 sc1
	s_nop 1
	global_load_dwordx4 v[16:19], v131, s[60:61] offset:576
	s_waitcnt vmcnt(14)
	v_pk_add_f32 v[64:65], v[64:65], v[216:217] op_sel_hi:[1,0] neg_lo:[0,1] neg_hi:[0,1]
	v_pk_add_f32 v[66:67], v[66:67], v[216:217] op_sel_hi:[1,0] neg_lo:[0,1] neg_hi:[0,1]
	v_pk_mul_f32 v[64:65], v[64:65], v[216:217] op_sel:[0,1] op_sel_hi:[1,1]
	v_pk_mul_f32 v[66:67], v[66:67], v[216:217] op_sel:[0,1] op_sel_hi:[1,1]
	v_pk_fma_f32 v[64:65], v[232:233], v[64:65], v[236:237]
	v_pk_fma_f32 v[66:67], v[234:235], v[66:67], v[238:239]
	v_pk_fma_f32 v[44:45], v[64:65], s[82:83], v[44:45] op_sel_hi:[1,0,1]
	v_pk_fma_f32 v[46:47], v[66:67], s[82:83], v[46:47] op_sel_hi:[1,0,1]
	s_nop 0
	global_store_dwordx4 v128, v[44:47], s[60:61] offset:512 sc1
	s_nop 1
	s_waitcnt vmcnt(13)
	v_pk_add_f32 v[32:33], v[32:33], v[216:217] op_sel_hi:[1,0] neg_lo:[0,1] neg_hi:[0,1]
	v_pk_add_f32 v[34:35], v[34:35], v[216:217] op_sel_hi:[1,0] neg_lo:[0,1] neg_hi:[0,1]
	v_pk_mul_f32 v[32:33], v[32:33], v[216:217] op_sel:[0,1] op_sel_hi:[1,1]
	v_pk_mul_f32 v[34:35], v[34:35], v[216:217] op_sel:[0,1] op_sel_hi:[1,1]
	v_pk_fma_f32 v[32:33], v[240:241], v[32:33], v[244:245]
	v_pk_fma_f32 v[34:35], v[242:243], v[34:35], v[246:247]
	v_pk_fma_f32 v[12:13], v[32:33], s[82:83], v[12:13] op_sel_hi:[1,0,1]
	v_pk_fma_f32 v[14:15], v[34:35], s[82:83], v[14:15] op_sel_hi:[1,0,1]
	s_nop 0
	global_store_dwordx4 v128, v[12:15], s[60:61] offset:576 sc1
	s_nop 1
	s_waitcnt vmcnt(12)
	v_pk_add_f32 v[56:57], v[56:57], v[218:219] op_sel_hi:[1,0] neg_lo:[0,1] neg_hi:[0,1]
	v_pk_add_f32 v[58:59], v[58:59], v[218:219] op_sel_hi:[1,0] neg_lo:[0,1] neg_hi:[0,1]
	v_pk_mul_f32 v[56:57], v[56:57], v[218:219] op_sel:[0,1] op_sel_hi:[1,1]
	v_pk_mul_f32 v[58:59], v[58:59], v[218:219] op_sel:[0,1] op_sel_hi:[1,1]
	v_pk_fma_f32 v[56:57], v[232:233], v[56:57], v[236:237]
	v_pk_fma_f32 v[58:59], v[234:235], v[58:59], v[238:239]
	v_pk_fma_f32 v[40:41], v[56:57], s[82:83], v[40:41] op_sel_hi:[1,0,1]
	v_pk_fma_f32 v[42:43], v[58:59], s[82:83], v[42:43] op_sel_hi:[1,0,1]
	s_nop 0
	global_store_dwordx4 v129, v[40:43], s[60:61] offset:512 sc1
	s_nop 1
	s_waitcnt vmcnt(11)
	v_pk_add_f32 v[24:25], v[24:25], v[218:219] op_sel_hi:[1,0] neg_lo:[0,1] neg_hi:[0,1]
	v_pk_add_f32 v[26:27], v[26:27], v[218:219] op_sel_hi:[1,0] neg_lo:[0,1] neg_hi:[0,1]
	v_pk_mul_f32 v[24:25], v[24:25], v[218:219] op_sel:[0,1] op_sel_hi:[1,1]
	v_pk_mul_f32 v[26:27], v[26:27], v[218:219] op_sel:[0,1] op_sel_hi:[1,1]
	v_pk_fma_f32 v[24:25], v[240:241], v[24:25], v[244:245]
	v_pk_fma_f32 v[26:27], v[242:243], v[26:27], v[246:247]
	v_pk_fma_f32 v[8:9], v[24:25], s[82:83], v[8:9] op_sel_hi:[1,0,1]
	v_pk_fma_f32 v[10:11], v[26:27], s[82:83], v[10:11] op_sel_hi:[1,0,1]
	s_nop 0
	global_store_dwordx4 v129, v[8:11], s[60:61] offset:576 sc1
	s_nop 1
	s_waitcnt vmcnt(10)
	v_pk_add_f32 v[52:53], v[52:53], v[220:221] op_sel_hi:[1,0] neg_lo:[0,1] neg_hi:[0,1]
	v_pk_add_f32 v[54:55], v[54:55], v[220:221] op_sel_hi:[1,0] neg_lo:[0,1] neg_hi:[0,1]
	v_pk_mul_f32 v[52:53], v[52:53], v[220:221] op_sel:[0,1] op_sel_hi:[1,1]
	v_pk_mul_f32 v[54:55], v[54:55], v[220:221] op_sel:[0,1] op_sel_hi:[1,1]
	v_pk_fma_f32 v[52:53], v[232:233], v[52:53], v[236:237]
	v_pk_fma_f32 v[54:55], v[234:235], v[54:55], v[238:239]
	v_pk_fma_f32 v[36:37], v[52:53], s[82:83], v[36:37] op_sel_hi:[1,0,1]
	v_pk_fma_f32 v[38:39], v[54:55], s[82:83], v[38:39] op_sel_hi:[1,0,1]
	s_nop 0
	global_store_dwordx4 v130, v[36:39], s[60:61] offset:512 sc1
	s_nop 1
	s_waitcnt vmcnt(9)
	v_pk_add_f32 v[20:21], v[20:21], v[220:221] op_sel_hi:[1,0] neg_lo:[0,1] neg_hi:[0,1]
	v_pk_add_f32 v[22:23], v[22:23], v[220:221] op_sel_hi:[1,0] neg_lo:[0,1] neg_hi:[0,1]
	v_pk_mul_f32 v[20:21], v[20:21], v[220:221] op_sel:[0,1] op_sel_hi:[1,1]
	v_pk_mul_f32 v[22:23], v[22:23], v[220:221] op_sel:[0,1] op_sel_hi:[1,1]
	v_pk_fma_f32 v[20:21], v[240:241], v[20:21], v[244:245]
	v_pk_fma_f32 v[22:23], v[242:243], v[22:23], v[246:247]
	v_pk_fma_f32 v[4:5], v[20:21], s[82:83], v[4:5] op_sel_hi:[1,0,1]
	v_pk_fma_f32 v[6:7], v[22:23], s[82:83], v[6:7] op_sel_hi:[1,0,1]
	s_nop 0
	global_store_dwordx4 v130, v[4:7], s[60:61] offset:576 sc1
	s_nop 1
	s_waitcnt vmcnt(8)
	v_pk_add_f32 v[48:49], v[48:49], v[230:231] op_sel_hi:[1,0] neg_lo:[0,1] neg_hi:[0,1]
	v_pk_add_f32 v[50:51], v[50:51], v[230:231] op_sel_hi:[1,0] neg_lo:[0,1] neg_hi:[0,1]
	v_pk_mul_f32 v[48:49], v[48:49], v[230:231] op_sel:[0,1] op_sel_hi:[1,1]
	v_pk_mul_f32 v[50:51], v[50:51], v[230:231] op_sel:[0,1] op_sel_hi:[1,1]
	v_pk_fma_f32 v[48:49], v[232:233], v[48:49], v[236:237]
	v_pk_fma_f32 v[50:51], v[234:235], v[50:51], v[238:239]
	v_pk_fma_f32 v[28:29], v[48:49], s[82:83], v[28:29] op_sel_hi:[1,0,1]
	v_pk_fma_f32 v[30:31], v[50:51], s[82:83], v[30:31] op_sel_hi:[1,0,1]
	s_nop 0
	global_store_dwordx4 v131, v[28:31], s[60:61] offset:512 sc1
	s_nop 1
	s_waitcnt vmcnt(7)
	v_pk_add_f32 v[16:17], v[16:17], v[230:231] op_sel_hi:[1,0] neg_lo:[0,1] neg_hi:[0,1]
	v_pk_add_f32 v[18:19], v[18:19], v[230:231] op_sel_hi:[1,0] neg_lo:[0,1] neg_hi:[0,1]
	v_pk_mul_f32 v[16:17], v[16:17], v[230:231] op_sel:[0,1] op_sel_hi:[1,1]
	v_pk_mul_f32 v[18:19], v[18:19], v[230:231] op_sel:[0,1] op_sel_hi:[1,1]
	v_pk_fma_f32 v[16:17], v[240:241], v[16:17], v[244:245]
	v_pk_fma_f32 v[18:19], v[242:243], v[18:19], v[246:247]
	v_pk_fma_f32 v[0:1], v[16:17], s[82:83], v[0:1] op_sel_hi:[1,0,1]
	v_pk_fma_f32 v[2:3], v[18:19], s[82:83], v[2:3] op_sel_hi:[1,0,1]
	s_nop 0
	global_store_dwordx4 v131, v[0:3], s[60:61] offset:576 sc1
	s_nop 1
	s_nop 3
	s_mov_b64 s[60:61], -1
	s_andn2_b64 vcc, exec, s[36:37]
	s_cbranch_vccnz .LBB0_1075
	s_andn2_b64 vcc, exec, s[48:49]
	s_cbranch_vccnz .LBB0_1074
	s_barrier
	s_branch .LBB0_1074
